# attention epilogues: silu-gate loads hoisted out of the store-load-wait chain; inproj requests the next item's first tile during the last K-step
# speedup vs baseline: 1.2357x; 1.0036x over previous
; #define G_STORE(S, bf) { *(uint4*)&s->a[bf][srow][skc] = S##a0; *(uint4*)&s->a[bf][srow + 32][skc] = S##a1; \
;     if (MB == 2) { *(uint4*)&s->a[bf][srow + 64][skc] = S##a2; *(uint4*)&s->a[bf][srow + 96][skc] = S##a3; } \
;     *(uint4*)&s->b[bf][srow][skc] = S##b0; *(uint4*)&s->b[bf][srow + 32][skc] = S##b1; *(uint4*)&s->b[bf][srow + 64][skc] = S##b2; *(uint4*)&s->b[bf][srow + 96][skc] = S##b3; }
; template <int MB, bool PF2 = true>
; DI void gemm_main(const u16* __restrict__ A, int lda, const u16* __restrict__ B, int ldb, int K, f32x16 (&acc)[MB][2], GemmLds* s, int tid) {
;   const int lane = tid & 63, w = tid >> 6, r = lane & 31, h = lane >> 5, wm = w >> 1, wn = w & 1;
;   const int srow = tid >> 3, skc = (tid & 7) * 8;
;   const unsigned oa0 = (unsigned)(srow * lda + skc) * 2u, oa1 = oa0 + 64u * lda, oa2 = oa0 + 128u * lda, oa3 = oa0 + 192u * lda;
;   const unsigned ob0 = (unsigned)(srow * ldb + skc) * 2u, ob1 = ob0 + 64u * ldb, ob2 = ob0 + 128u * ldb, ob3 = ob0 + 192u * ldb;
;   uint4 pa0, pa1, pa2, pa3, pb0, pb1, pb2, pb3, qa0, qa1, qa2, qa3, qb0, qb1, qb2, qb3;
;   pa2 = pa3 = qa2 = qa3 = make_uint4(0, 0, 0, 0);
;     ...
;   int KT = K >> 6;
;   asm volatile("" : "+s"(KT));
;   __syncthreads();
;   G_LOAD(p, 0); G_STORE(p, 0);
; DI void phase_inproj(const Params& p, int l, char* smem, int tid) {
;   const int lane = tid & 63, w = tid >> 6, r = lane & 31, h = lane >> 5, wm = w >> 1, wn = w & 1;
;   GemmLds* s = (GemmLds*)smem;
;   const u16* Wt = p.WtIn + (size_t)l * 3072 * 1024;
;   for (int it = blockIdx.x; it < 272 * 24; it += gridDim.x) {
;     const int mt = it / 24, nt = it % 24, m0 = mt * 128, n0 = nt * 128;
;     f32x16 acc[2][2]; zero_acc<2>(acc);
;     gemm_main<2>(p.xn + (size_t)m0 * 1024, 1024, Wt + (size_t)n0 * 1024, 1024, 1024, acc, s, tid);
.LBB0_515:
	v_readlane_b32 s0, v253, 14
	v_readlane_b32 s1, v253, 15
	v_mov_b32_e32 v0, v206
	s_andn2_b64 vcc, exec, s[0:1]
	s_cbranch_vccnz .LBB0_550
	v_readlane_b32 s0, v254, 19
	v_and_b32_e32 v113, 63, v206
	v_lshrrev_b32_e32 v114, 6, v206
	v_lshrrev_b32_e32 v115, 3, v113
	v_lshl_add_u32 v115, v114, 5, v115
	v_lshlrev_b32_e32 v115, 11, v115
	v_and_b32_e32 v116, 7, v113
	v_lshrrev_b32_e32 v113, 4, v113
	v_xor_b32_e32 v116, v116, v113
	v_lshl_or_b32 v98, v116, 4, v115
	v_xor_b32_e32 v99, 64, v98
	v_add_u32_e32 v99, 16384, v99
	v_add_u32_e32 v100, 32768, v98
	v_add_u32_e32 v101, 32768, v99
	v_lshrrev_b32_e32 v117, 6, v206
	v_and_b32_e32 v113, 31, v206
	v_bfe_u32 v114, v206, 5, 1
	v_bfe_u32 v115, v113, 1, 3
	v_xor_b32_e32 v115, v115, v114
	v_lshlrev_b32_e32 v115, 4, v115
	v_lshl_or_b32 v115, v113, 7, v115
	v_lshrrev_b32_e32 v116, 7, v206
	v_lshl_add_u32 v102, v116, 13, v115
	v_bfe_u32 v116, v206, 6, 1
	v_lshl_add_u32 v106, v116, 13, v115
	v_add_u32_e32 v106, 0x4000, v106
	v_xor_b32_e32 v103, 32, v102
	v_xor_b32_e32 v107, 32, v106
	v_xor_b32_e32 v104, 64, v102
	v_xor_b32_e32 v108, 64, v106
	v_xor_b32_e32 v105, 96, v102
	v_xor_b32_e32 v109, 96, v106
	v_and_b32_e32 v113, 31, v206
	v_lshrrev_b32_e32 v114, 7, v206
	v_lshl_add_u32 v113, v114, 6, v113
	v_bfe_u32 v115, v206, 5, 1
	v_lshlrev_b32_e32 v116, 3, v115
	v_mul_u32_u24_e32 v110, 0xe00, v113
	v_add_u32_e32 v110, v110, v116
	v_mul_u32_u24_e32 v111, 0x640, v113
	v_add_u32_e32 v111, v111, v116
	v_mul_u32_u24_e32 v116, 0x8800, v115
	v_lshl_add_u32 v112, v113, 1, v116
	v_lshrrev_b32_e32 v113, 6, v206
	v_mul_u32_u24_e32 v113, 0x2400, v113
	v_add_u32_e32 v113, 0x8000, v113
	v_and_b32_e32 v114, 31, v206
	v_mul_u32_u24_e32 v114, 0x90, v114
	v_bfe_u32 v115, v206, 5, 1
	v_lshl_add_u32 v114, v115, 3, v114
	v_add_u32_e32 v118, v113, v114
	v_bfe_u32 v114, v206, 3, 3
	v_mul_u32_u24_e32 v114, 0x90, v114
	v_and_b32_e32 v115, 7, v206
	v_lshl_add_u32 v114, v115, 4, v114
	v_add_u32_e32 v119, v113, v114
	v_bfe_u32 v113, v206, 3, 3
	v_lshrrev_b32_e32 v114, 7, v206
	v_lshl_add_u32 v113, v114, 6, v113
	v_mul_u32_u24_e32 v113, 0xe00, v113
	v_bfe_u32 v114, v206, 6, 1
	v_lshlrev_b32_e32 v114, 7, v114
	v_and_b32_e32 v115, 7, v206
	v_lshl_or_b32 v114, v115, 4, v114
	v_add_u32_e32 v120, v113, v114
	v_bfe_u32 v113, v206, 3, 3
	v_lshrrev_b32_e32 v114, 7, v206
	v_lshl_add_u32 v113, v114, 6, v113
	v_mul_u32_u24_e32 v113, 0x640, v113
	v_bfe_u32 v114, v206, 6, 1
	v_lshlrev_b32_e32 v114, 7, v114
	v_and_b32_e32 v115, 7, v206
	v_lshl_or_b32 v114, v115, 4, v114
	v_add_u32_e32 v121, v113, v114
	v_readfirstlane_b32 s10, v117
	s_lshl_b32 s10, s10, 12
	s_mul_i32 s1, s0, 0x600000
	s_add_u32 s14, s96, 0x1ab20000
	s_addc_u32 s15, s97, 0
	s_add_u32 s14, s14, s1
	s_addc_u32 s15, s15, 0
	s_mov_b32 s12, s48
	s_cmpk_lt_u32 s12, 0x1980
	s_cbranch_scc0 .Lip_done
	s_mul_hi_u32 s0, s12, 0xaaaaaaab
	s_lshr_b32 s0, s0, 4
	s_mul_i32 s1, s0, 24
	s_sub_u32 s1, s12, s1
	s_lshl_b32 s2, s0, 18
	s_add_u32 s4, s96, s2
	s_addc_u32 s5, s97, 0
	s_lshl_b32 s2, s1, 18
	s_add_u32 s8, s14, s2
	s_addc_u32 s9, s15, 0
	s_add_u32 m0, s10, 0x0
	s_nop 0
	global_load_lds_dwordx4 v98, s[4:5]
	s_add_u32 m0, s10, 0x400
	s_nop 0
	global_load_lds_dwordx4 v99, s[4:5]
	s_add_u32 m0, s10, 0x800
	s_nop 0
	global_load_lds_dwordx4 v100, s[4:5]
	s_add_u32 m0, s10, 0xc00
	s_nop 0
	global_load_lds_dwordx4 v101, s[4:5]
	s_add_u32 m0, s10, 0x4000
	s_nop 0
	global_load_lds_dwordx4 v98, s[8:9]
	s_add_u32 m0, s10, 0x4400
	s_nop 0
	global_load_lds_dwordx4 v99, s[8:9]
	s_add_u32 m0, s10, 0x4800
	s_nop 0
	global_load_lds_dwordx4 v100, s[8:9]
	s_add_u32 m0, s10, 0x4c00
	s_nop 0
	global_load_lds_dwordx4 v101, s[8:9]
	s_add_u32 s4, s4, 128
	s_addc_u32 s5, s5, 0
	s_add_u32 s8, s8, 128
	s_addc_u32 s9, s9, 0
.Lip_item:
	s_mul_hi_u32 s0, s12, 0xaaaaaaab
	s_lshr_b32 s0, s0, 4
	s_mul_i32 s1, s0, 24
	s_sub_u32 s1, s12, s1
	s_mov_b32 s94, 0
.Lip_again:
	v_mov_b32_e32 v2, 0
	v_mov_b32_e32 v3, 0
	v_mov_b32_e32 v4, 0
	v_mov_b32_e32 v5, 0
	v_mov_b32_e32 v6, 0
	v_mov_b32_e32 v7, 0
	v_mov_b32_e32 v8, 0
	v_mov_b32_e32 v9, 0
	v_mov_b32_e32 v10, 0
	v_mov_b32_e32 v11, 0
	v_mov_b32_e32 v12, 0
	v_mov_b32_e32 v13, 0
	v_mov_b32_e32 v14, 0
	v_mov_b32_e32 v15, 0
	v_mov_b32_e32 v16, 0
	v_mov_b32_e32 v17, 0
	v_mov_b32_e32 v18, 0
	v_mov_b32_e32 v19, 0
	v_mov_b32_e32 v20, 0
	v_mov_b32_e32 v21, 0
	v_mov_b32_e32 v22, 0
	v_mov_b32_e32 v23, 0
	v_mov_b32_e32 v24, 0
	v_mov_b32_e32 v25, 0
	v_mov_b32_e32 v26, 0
	v_mov_b32_e32 v27, 0
	v_mov_b32_e32 v28, 0
	v_mov_b32_e32 v29, 0
	v_mov_b32_e32 v30, 0
	v_mov_b32_e32 v31, 0
	v_mov_b32_e32 v32, 0
	v_mov_b32_e32 v33, 0
	v_mov_b32_e32 v34, 0
	v_mov_b32_e32 v35, 0
	v_mov_b32_e32 v36, 0
	v_mov_b32_e32 v37, 0
	v_mov_b32_e32 v38, 0
	v_mov_b32_e32 v39, 0
	v_mov_b32_e32 v40, 0
	v_mov_b32_e32 v41, 0
	v_mov_b32_e32 v42, 0
	v_mov_b32_e32 v43, 0
	v_mov_b32_e32 v44, 0
	v_mov_b32_e32 v45, 0
	v_mov_b32_e32 v46, 0
	v_mov_b32_e32 v47, 0
	v_mov_b32_e32 v48, 0
	v_mov_b32_e32 v49, 0
	v_mov_b32_e32 v50, 0
	v_mov_b32_e32 v51, 0
	v_mov_b32_e32 v52, 0
	v_mov_b32_e32 v53, 0
	v_mov_b32_e32 v54, 0
	v_mov_b32_e32 v55, 0
	v_mov_b32_e32 v56, 0
	v_mov_b32_e32 v57, 0
	v_mov_b32_e32 v58, 0
	v_mov_b32_e32 v59, 0
	v_mov_b32_e32 v60, 0
	v_mov_b32_e32 v61, 0
	v_mov_b32_e32 v62, 0
	v_mov_b32_e32 v63, 0
	v_mov_b32_e32 v64, 0
	v_mov_b32_e32 v65, 0
	s_waitcnt vmcnt(0) lgkmcnt(0)
	s_barrier
	ds_read_b128 v[66:69], v102 offset:0
	ds_read_b128 v[74:77], v106 offset:0
	ds_read_b128 v[70:73], v102 offset:4096
	ds_read_b128 v[78:81], v106 offset:4096
	s_add_u32 m0, s10, 0x8000
	s_nop 0
	global_load_lds_dwordx4 v98, s[4:5]
	s_add_u32 m0, s10, 0x8400
	s_nop 0
	global_load_lds_dwordx4 v99, s[4:5]
	s_add_u32 m0, s10, 0x8800
	s_nop 0
	global_load_lds_dwordx4 v100, s[4:5]
	s_add_u32 m0, s10, 0x8c00
	s_nop 0
	global_load_lds_dwordx4 v101, s[4:5]
	s_add_u32 s4, s4, 128
	s_addc_u32 s5, s5, 0
	s_mov_b32 s11, 7

; #define G_STORE(S, bf) { *(uint4*)&s->a[bf][srow][skc] = S##a0; *(uint4*)&s->a[bf][srow + 32][skc] = S##a1; \
;     if (MB == 2) { *(uint4*)&s->a[bf][srow + 64][skc] = S##a2; *(uint4*)&s->a[bf][srow + 96][skc] = S##a3; } \
;     *(uint4*)&s->b[bf][srow][skc] = S##b0; *(uint4*)&s->b[bf][srow + 32][skc] = S##b1; *(uint4*)&s->b[bf][srow + 64][skc] = S##b2; *(uint4*)&s->b[bf][srow + 96][skc] = S##b3; }
; template <int MB, bool PF2 = true>
; DI void gemm_main(const u16* __restrict__ A, int lda, const u16* __restrict__ B, int ldb, int K, f32x16 (&acc)[MB][2], GemmLds* s, int tid) {
;     ...
;   for (int kt = 0; kt < KT; kt += 2) {
;     { const int k2 = min((kt + 2) * 64, klast); G_LOAD(q, k2); }
;     __builtin_amdgcn_sched_barrier(0);
;     G_COMPUTE(0);
;     G_STORE(p, 1);
;     __syncthreads();
;     { const int k3 = min((kt + 3) * 64, klast); G_LOAD(p, k3); }
;     __builtin_amdgcn_sched_barrier(0);
;     G_COMPUTE(1);
;     G_STORE(q, 0);
;     __syncthreads();
; DI void phase_inproj(const Params& p, int l, char* smem, int tid) {
;     ...
;   for (int it = blockIdx.x; it < 272 * 24; it += gridDim.x) {
;     const int mt = it / 24, nt = it % 24, m0 = mt * 128, n0 = nt * 128;
;     f32x16 acc[2][2]; zero_acc<2>(acc);
;     gemm_main<2>(p.xn + (size_t)m0 * 1024, 1024, Wt + (size_t)n0 * 1024, 1024, 1024, acc, s, tid);
; #pragma unroll
;     for (int mb = 0; mb < 2; mb++)
; #pragma unroll
;       for (int nb = 0; nb < 2; nb++) {
;         const int rowb = m0 + wm * 64 + mb * 32, colb = n0 + wn * 64 + nb * 32, col = colb + r;
;         if (colb < 1792) {
.Lip_last:
	s_add_u32 s6, s12, s49
	s_cmpk_lt_u32 s6, 0x1980
	s_cbranch_scc0 .Lip_nopf
	s_mul_hi_u32 s2, s6, 0xaaaaaaab
	s_lshr_b32 s2, s2, 4
	s_mul_i32 s3, s2, 24
	s_sub_u32 s3, s6, s3
	s_lshl_b32 s2, s2, 18
	s_add_u32 s4, s96, s2
	s_addc_u32 s5, s97, 0
	s_lshl_b32 s3, s3, 18
	s_add_u32 s8, s14, s3
	s_addc_u32 s9, s15, 0
	s_add_u32 m0, s10, 0x0
	s_nop 0
	global_load_lds_dwordx4 v98, s[4:5]
	s_add_u32 m0, s10, 0x400
	s_nop 0
	global_load_lds_dwordx4 v99, s[4:5]
	s_add_u32 m0, s10, 0x800
	s_nop 0
	global_load_lds_dwordx4 v100, s[4:5]
	s_add_u32 m0, s10, 0xc00
	s_nop 0
	global_load_lds_dwordx4 v101, s[4:5]
	s_add_u32 m0, s10, 0x4000
	s_nop 0
	global_load_lds_dwordx4 v98, s[8:9]
	s_add_u32 m0, s10, 0x4400
	s_nop 0
	global_load_lds_dwordx4 v99, s[8:9]
	s_add_u32 m0, s10, 0x4800
	s_nop 0
	global_load_lds_dwordx4 v100, s[8:9]
	s_add_u32 m0, s10, 0x4c00
	s_nop 0
	global_load_lds_dwordx4 v101, s[8:9]
	s_add_u32 s4, s4, 128
	s_addc_u32 s5, s5, 0
	s_add_u32 s8, s8, 128
	s_addc_u32 s9, s9, 0
.Lip_nopf:
	ds_read_b128 v[82:85], v103 offset:32768
	ds_read_b128 v[90:93], v107 offset:32768
	ds_read_b128 v[86:89], v103 offset:36864
	ds_read_b128 v[94:97], v107 offset:36864
	s_waitcnt lgkmcnt(4)
	v_mfma_f32_32x32x16_bf16 v[2:17], v[74:77], v[66:69], v[2:17]
	v_mfma_f32_32x32x16_bf16 v[18:33], v[78:81], v[66:69], v[18:33]
	v_mfma_f32_32x32x16_bf16 v[34:49], v[74:77], v[70:73], v[34:49]
	v_mfma_f32_32x32x16_bf16 v[50:65], v[78:81], v[70:73], v[50:65]
	ds_read_b128 v[66:69], v104 offset:32768
	ds_read_b128 v[74:77], v108 offset:32768
	ds_read_b128 v[70:73], v104 offset:36864
	ds_read_b128 v[78:81], v108 offset:36864
	s_waitcnt lgkmcnt(4)
	v_mfma_f32_32x32x16_bf16 v[2:17], v[90:93], v[82:85], v[2:17]
	v_mfma_f32_32x32x16_bf16 v[18:33], v[94:97], v[82:85], v[18:33]
	v_mfma_f32_32x32x16_bf16 v[34:49], v[90:93], v[86:89], v[34:49]
	v_mfma_f32_32x32x16_bf16 v[50:65], v[94:97], v[86:89], v[50:65]
	ds_read_b128 v[82:85], v105 offset:32768
	ds_read_b128 v[90:93], v109 offset:32768
	ds_read_b128 v[86:89], v105 offset:36864
	ds_read_b128 v[94:97], v109 offset:36864
	s_waitcnt lgkmcnt(4)
	v_mfma_f32_32x32x16_bf16 v[2:17], v[74:77], v[66:69], v[2:17]
	v_mfma_f32_32x32x16_bf16 v[18:33], v[78:81], v[66:69], v[18:33]
	v_mfma_f32_32x32x16_bf16 v[34:49], v[74:77], v[70:73], v[34:49]
	v_mfma_f32_32x32x16_bf16 v[50:65], v[78:81], v[70:73], v[50:65]
	s_waitcnt lgkmcnt(0)
	s_barrier
	v_mfma_f32_32x32x16_bf16 v[2:17], v[90:93], v[82:85], v[2:17]
	v_mfma_f32_32x32x16_bf16 v[18:33], v[94:97], v[82:85], v[18:33]
	v_mfma_f32_32x32x16_bf16 v[34:49], v[90:93], v[86:89], v[34:49]
	v_mfma_f32_32x32x16_bf16 v[50:65], v[94:97], v[86:89], v[50:65]
	s_nop 7
	s_nop 7
	s_bfe_u32 s2, s10, 0x1000c
	s_lshl_b32 s2, s2, 6
	s_lshl_b32 s16, s1, 7
	s_add_u32 s16, s16, s2
	s_cmpk_lt_u32 s16, 0x700
	s_cbranch_scc1 .Lip_rows_pk
	s_cmpk_lt_u32 s16, 0x9e1
	s_cbranch_scc1 .Lip_rows_pt
	s_branch .Lip_generic

; DI void phase_inproj(const Params& p, int l, char* smem, int tid) {
;     ...
;   for (int it = blockIdx.x; it < 272 * 24; it += gridDim.x) {
.Lip_e1_end:
.Lip_epi_done:
	s_add_u32 s12, s12, s49
	s_cmpk_lt_u32 s12, 0x1980
	s_cbranch_scc1 .Lip_item

; #define MFMA(a, b, c) __builtin_amdgcn_mfma_f32_32x32x16_bf16((a), (b), (c), 0, 0, 0)
; DI unsigned pack2(float a, float b) { f32v2 v = {a, b}; return __builtin_bit_cast(unsigned, __builtin_convertvector(v, bf16v2)); }
; DI float bflo(unsigned v) { return __uint_as_float(v << 16); }
; DI float bfhi(unsigned v) { return __uint_as_float(v & 0xffff0000u); }
; DI float silu(float x) { return x * sigm(x); }
; DI float xhalf_sum(float v) { auto r = __builtin_amdgcn_permlane32_swap(__float_as_uint(v), __float_as_uint(v), false, false); return __uint_as_float(r[0]) + __uint_as_float(r[1]); }
; template <int DK>
; DI void attn_item2(const u16* __restrict__ Q, int ldq, const u16* __restrict__ K, int ldk, const u16* __restrict__ Vt, int nTiles,
;                    u16* __restrict__ Gp, const u16* __restrict__ Zp, char* smem, int tid) {
;     ...
;       SOFTMAX_STEP(s0, m_run0, l_run0, o[0], pf0)
;       SOFTMAX_STEP(s1, m_run1, l_run1, o[1], pf1)
;     ...
; #pragma unroll
;       for (int db = 0; db < 2; db++)
; #pragma unroll
;         for (int sx = 0; sx < 2; sx++) {
;           const u16* vp = &Vs[buf][db * 32 + r][32 * kb + 16 * sx + 4 * h];
;           uint2 lo = *(const uint2*)vp, hi = *(const uint2*)(vp + 8);
;           uint4 u; u.x = lo.x; u.y = lo.y; u.z = hi.x; u.w = hi.y;
;           const bf16x8 a = __builtin_bit_cast(bf16x8, u);
;           o[0][db] = MFMA(a, pf0[sx], o[0][db]);
;           o[1][db] = MFMA(a, pf1[sx], o[1][db]);
;         }
;     }
;     if (t + 1 < nTiles) LSTORE(buf ^ 1);
;     __syncthreads();
;   }
;     ...
; #pragma unroll
;   for (int qw = 0; qw < 2; qw++) {
;     const float inv = __builtin_amdgcn_rcpf(xhalf_sum(qw ? l_run1 : l_run0));
;     const int q = (w * 2 + qw) * 32 + r;
; #pragma unroll
;     for (int db = 0; db < 2; db++)
; #pragma unroll
;       for (int g = 0; g < 4; g++) {
;         const int d0 = 32 * db + 8 * g + 4 * h;
;         uint2 zz = *(const uint2*)(Zp + (size_t)q * PKW + d0);
;         uint2 ov; ov.x = pack2(o[qw][db][4 * g] * inv * silu(bflo(zz.x)), o[qw][db][4 * g + 1] * inv * silu(bfhi(zz.x)));
;         ov.y = pack2(o[qw][db][4 * g + 2] * inv * silu(bflo(zz.y)), o[qw][db][4 * g + 3] * inv * silu(bfhi(zz.y)));
;         *(uint2*)(Gp + (size_t)q * 1024 + d0) = ov;
.LBB0_878:
	v_sub_f32_e32 v0, v96, v191
	v_exp_f32_e32 v113, v0
	v_sub_f32_e32 v0, v97, v191
	v_exp_f32_e32 v114, v0
	v_sub_f32_e32 v0, v98, v191
	v_exp_f32_e32 v98, v0
	v_sub_f32_e32 v0, v99, v191
	v_exp_f32_e32 v99, v0
	v_sub_f32_e32 v0, v100, v191
	v_exp_f32_e32 v100, v0
	v_sub_f32_e32 v0, v101, v191
	v_exp_f32_e32 v101, v0
	v_sub_f32_e32 v0, v102, v191
	v_exp_f32_e32 v102, v0
	v_sub_f32_e32 v0, v103, v191
	v_exp_f32_e32 v103, v0
	v_sub_f32_e32 v0, v104, v191
	v_exp_f32_e32 v104, v0
	v_sub_f32_e32 v0, v105, v191
	v_exp_f32_e32 v105, v0
	v_sub_f32_e32 v0, v106, v191
	v_exp_f32_e32 v106, v0
	v_sub_f32_e32 v0, v107, v191
	v_exp_f32_e32 v107, v0
	v_sub_f32_e32 v0, v108, v191
	v_exp_f32_e32 v108, v0
	v_sub_f32_e32 v0, v109, v191
	v_readlane_b32 s2, v253, 48
	v_exp_f32_e32 v109, v0
	v_sub_f32_e32 v0, v110, v191
	v_lshlrev_b64 v[10:11], 11, v[194:195]
	v_readlane_b32 s3, v253, 49
	v_mov_b64_e32 v[12:13], s[90:91]
	v_exp_f32_e32 v110, v0
	v_sub_f32_e32 v0, v111, v191
	v_lshl_add_u64 v[10:11], s[2:3], 0, v[10:11]
	v_mad_u64_u32 v[12:13], s[2:3], v194, s33, v[12:13]
	v_exp_f32_e32 v111, v0
	v_mov_b32_e32 v0, v13
	v_mad_u64_u32 v[14:15], s[2:3], v195, s33, v[0:1]
	v_lshlrev_b32_e32 v0, 1, v196
	v_mov_b32_e32 v13, v14
	v_lshl_add_u64 v[14:15], v[10:11], 0, v[0:1]
	v_sub_f32_e32 v10, v81, v189
	v_exp_f32_e32 v115, v10
	v_sub_f32_e32 v10, v82, v189
	v_exp_f32_e32 v116, v10
	v_sub_f32_e32 v10, v83, v189
	v_exp_f32_e32 v117, v10
	v_sub_f32_e32 v10, v84, v189
	v_exp_f32_e32 v118, v10
	v_sub_f32_e32 v10, v85, v189
	v_exp_f32_e32 v119, v10
	v_sub_f32_e32 v10, v86, v189
	v_exp_f32_e32 v120, v10
	v_sub_f32_e32 v10, v87, v189
	v_exp_f32_e32 v121, v10
	v_sub_f32_e32 v10, v88, v189
	v_exp_f32_e32 v122, v10
	v_sub_f32_e32 v10, v89, v189
	v_exp_f32_e32 v123, v10
	v_sub_f32_e32 v10, v90, v189
	v_lshl_add_u64 v[96:97], v[12:13], 0, v[0:1]
	v_sub_f32_e32 v0, v80, v189
	v_exp_f32_e32 v124, v10
	v_sub_f32_e32 v10, v91, v189
	v_exp_f32_e32 v0, v0
	v_exp_f32_e32 v125, v10
	v_sub_f32_e32 v10, v92, v189
	v_exp_f32_e32 v92, v10
	v_sub_f32_e32 v10, v93, v189
	ds_read2_b64 v[84:87], v146 offset0:8 offset1:10
	ds_read2_b64 v[88:91], v146 offset0:12 offset1:14
	v_exp_f32_e32 v93, v10
	v_sub_f32_e32 v10, v94, v189
	v_exp_f32_e32 v94, v10
	v_sub_f32_e32 v10, v95, v189
	v_cvt_pk_bf16_f32 v6, v113, v114
	v_cvt_pk_bf16_f32 v7, v98, v99
	v_cvt_pk_bf16_f32 v8, v100, v101
	v_cvt_pk_bf16_f32 v9, v102, v103
	v_exp_f32_e32 v95, v10
	v_cvt_pk_bf16_f32 v10, v0, v115
	v_cvt_pk_bf16_f32 v11, v116, v117
	v_cvt_pk_bf16_f32 v12, v118, v119
	v_cvt_pk_bf16_f32 v13, v120, v121
	s_waitcnt lgkmcnt(1)
	v_mfma_f32_32x32x16_bf16 v[64:79], v[84:87], v[6:9], v[64:79]
	v_add_f32_e32 v0, 0, v0
	v_add_f32_e32 v0, v115, v0
	v_add_f32_e32 v0, v116, v0
	v_add_f32_e32 v0, v117, v0
	v_add_f32_e32 v0, v118, v0
	v_add_f32_e32 v0, v119, v0
	v_add_f32_e32 v0, v120, v0
	v_mfma_f32_32x32x16_bf16 v[32:47], v[84:87], v[10:13], v[32:47]
	ds_read2_b64 v[84:87], v145 offset0:40 offset1:42
	v_add_f32_e32 v0, v121, v0
	v_add_f32_e32 v0, v122, v0
	v_add_f32_e32 v0, v123, v0
	v_add_f32_e32 v0, v124, v0
	v_add_f32_e32 v0, v125, v0
	v_add_f32_e32 v0, v92, v0
	s_waitcnt lgkmcnt(0)
	v_mfma_f32_32x32x16_bf16 v[48:63], v[84:87], v[6:9], v[48:63]
	ds_read2_b64 v[6:9], v145 offset0:44 offset1:46
	v_add_f32_e32 v0, v93, v0
	v_add_f32_e32 v0, v94, v0
	v_cvt_pk_bf16_f32 v2, v104, v105
	v_cvt_pk_bf16_f32 v3, v106, v107
	v_cvt_pk_bf16_f32 v4, v108, v109
	v_cvt_pk_bf16_f32 v5, v110, v111
	v_mfma_f32_32x32x16_bf16 v[16:31], v[84:87], v[10:13], v[16:31]
	v_cvt_pk_bf16_f32 v80, v122, v123
	v_cvt_pk_bf16_f32 v81, v124, v125
	v_cvt_pk_bf16_f32 v82, v92, v93
	v_cvt_pk_bf16_f32 v83, v94, v95
	v_add_f32_e32 v0, v95, v0
	v_mov_b32_e32 v193, v1
	s_waitcnt lgkmcnt(0)
	v_mfma_f32_32x32x16_bf16 v[48:63], v[6:9], v[2:5], v[48:63]
	s_barrier
	v_mfma_f32_32x32x16_bf16 v[16:31], v[6:9], v[80:83], v[16:31]
	v_add_f32_e32 v6, v112, v0
	v_add_f32_e32 v0, 0, v113
	v_add_f32_e32 v0, v114, v0
	v_add_f32_e32 v0, v98, v0
	v_add_f32_e32 v0, v99, v0
	v_add_f32_e32 v0, v100, v0
	v_add_f32_e32 v0, v101, v0
	v_add_f32_e32 v0, v102, v0
	v_add_f32_e32 v0, v103, v0
	v_add_f32_e32 v0, v104, v0
	v_add_f32_e32 v0, v105, v0
	v_add_f32_e32 v0, v106, v0
	v_add_f32_e32 v0, v107, v0
	v_add_f32_e32 v0, v108, v0
	v_add_f32_e32 v0, v109, v0
	v_add_f32_e32 v0, v110, v0
	v_add_f32_e32 v0, v111, v0
	v_add_f32_e32 v0, v144, v0
	v_mfma_f32_32x32x16_bf16 v[64:79], v[88:91], v[2:5], v[64:79]
	v_mov_b32_e32 v2, v0
	s_nop 1
	v_permlane32_swap_b32_e32 v0, v2
	v_add_f32_e32 v0, v0, v2
	v_lshl_add_u64 v[2:3], v[96:97], 0, v[174:175]
	v_lshl_add_u64 v[2:3], v[2:3], 0, v[192:193]
	global_load_dwordx2 v[100:101], v[2:3], off offset:3072
	global_load_dwordx2 v[102:103], v[2:3], off offset:3088
	global_load_dwordx2 v[104:105], v[2:3], off offset:3104
	global_load_dwordx2 v[106:107], v[2:3], off offset:3120
	global_load_dwordx2 v[108:109], v[2:3], off offset:3136
	global_load_dwordx2 v[110:111], v[2:3], off offset:3152
	global_load_dwordx2 v[112:113], v[2:3], off offset:3168
	global_load_dwordx2 v[114:115], v[2:3], off offset:3184
	v_rcp_f32_e32 v0, v0
	v_lshl_add_u64 v[4:5], v[14:15], 0, v[176:177]
	v_lshl_add_u64 v[4:5], v[4:5], 0, v[192:193]
	v_mfma_f32_32x32x16_bf16 v[32:47], v[88:91], v[80:83], v[32:47]
	v_mul_f32_e64 v64, v64, v0
	v_mul_f32_e64 v65, v65, v0
	v_mul_f32_e64 v48, v48, v0
	v_mul_f32_e64 v49, v49, v0
	s_waitcnt vmcnt(0)
; DI unsigned pack2(float a, float b) { f32v2 v = {a, b}; return __builtin_bit_cast(unsigned, __builtin_convertvector(v, bf16v2)); }
; DI float bflo(unsigned v) { return __uint_as_float(v << 16); }
; DI float bfhi(unsigned v) { return __uint_as_float(v & 0xffff0000u); }
; DI float silu(float x) { return x * sigm(x); }
; DI float xhalf_sum(float v) { auto r = __builtin_amdgcn_permlane32_swap(__float_as_uint(v), __float_as_uint(v), false, false); return __uint_as_float(r[0]) + __uint_as_float(r[1]); }
; template <int DK>
; DI void attn_item2(const u16* __restrict__ Q, int ldq, const u16* __restrict__ K, int ldk, const u16* __restrict__ Vt, int nTiles,
;                    u16* __restrict__ Gp, const u16* __restrict__ Zp, char* smem, int tid) {
;     ...
; #pragma unroll
;   for (int qw = 0; qw < 2; qw++) {
;     const float inv = __builtin_amdgcn_rcpf(xhalf_sum(qw ? l_run1 : l_run0));
;     const int q = (w * 2 + qw) * 32 + r;
; #pragma unroll
;     for (int db = 0; db < 2; db++)
; #pragma unroll
;       for (int g = 0; g < 4; g++) {
;         const int d0 = 32 * db + 8 * g + 4 * h;
;         uint2 zz = *(const uint2*)(Zp + (size_t)q * PKW + d0);
;         uint2 ov; ov.x = pack2(o[qw][db][4 * g] * inv * silu(bflo(zz.x)), o[qw][db][4 * g + 1] * inv * silu(bfhi(zz.x)));
;         ov.y = pack2(o[qw][db][4 * g + 2] * inv * silu(bflo(zz.y)), o[qw][db][4 * g + 3] * inv * silu(bfhi(zz.y)));
;         *(uint2*)(Gp + (size_t)q * 1024 + d0) = ov;
;       }
	v_lshlrev_b32_e32 v10, 16, v100
	v_mul_f32_e32 v7, 0xbfb8aa3b, v10
	v_exp_f32_e32 v7, v7
	v_and_b32_e32 v11, 0xffff0000, v100
	v_add_f32_e32 v7, 1.0, v7
	v_rcp_f32_e32 v12, v7
	v_mul_f32_e32 v7, 0xbfb8aa3b, v11
	v_exp_f32_e32 v7, v7
	s_nop 0
	v_add_f32_e32 v7, 1.0, v7
	v_rcp_f32_e32 v13, v7
	s_nop 0
	v_pk_mul_f32 v[10:11], v[12:13], v[10:11]
	s_nop 0
	v_pk_mul_f32 v[10:11], v[64:65], v[10:11]
	v_pk_mul_f32 v[64:65], v[66:67], v[0:1] op_sel_hi:[1,0]
	v_cvt_pk_bf16_f32 v8, v10, v11
	v_lshlrev_b32_e32 v10, 16, v101
	v_mul_f32_e32 v7, 0xbfb8aa3b, v10
	v_exp_f32_e32 v7, v7
	v_and_b32_e32 v11, 0xffff0000, v101
	v_add_f32_e32 v7, 1.0, v7
	v_rcp_f32_e32 v12, v7
	v_mul_f32_e32 v7, 0xbfb8aa3b, v11
	v_exp_f32_e32 v7, v7
	s_nop 0
	v_add_f32_e32 v7, 1.0, v7
	v_rcp_f32_e32 v13, v7
	s_nop 0
	v_pk_mul_f32 v[10:11], v[12:13], v[10:11]
	s_nop 0
	v_pk_mul_f32 v[10:11], v[64:65], v[10:11]
	v_pk_mul_f32 v[64:65], v[68:69], v[0:1] op_sel_hi:[1,0]
	v_cvt_pk_bf16_f32 v9, v10, v11
	global_store_dwordx2 v[4:5], v[8:9], off offset:1536
	v_lshlrev_b32_e32 v10, 16, v102
	v_mul_f32_e32 v7, 0xbfb8aa3b, v10
	v_exp_f32_e32 v7, v7
	v_and_b32_e32 v11, 0xffff0000, v102
	v_add_f32_e32 v7, 1.0, v7
	v_rcp_f32_e32 v12, v7
	v_mul_f32_e32 v7, 0xbfb8aa3b, v11
	v_exp_f32_e32 v7, v7
	s_nop 0
	v_add_f32_e32 v7, 1.0, v7
	v_rcp_f32_e32 v13, v7
	s_nop 0
	v_pk_mul_f32 v[10:11], v[12:13], v[10:11]
	s_nop 0
	v_pk_mul_f32 v[10:11], v[64:65], v[10:11]
	v_pk_mul_f32 v[64:65], v[70:71], v[0:1] op_sel_hi:[1,0]
	v_cvt_pk_bf16_f32 v8, v10, v11
	v_lshlrev_b32_e32 v10, 16, v103
	v_mul_f32_e32 v7, 0xbfb8aa3b, v10
	v_exp_f32_e32 v7, v7
	v_and_b32_e32 v11, 0xffff0000, v103
	v_add_f32_e32 v7, 1.0, v7
	v_rcp_f32_e32 v12, v7
	v_mul_f32_e32 v7, 0xbfb8aa3b, v11
	v_exp_f32_e32 v7, v7
	s_nop 0
	v_add_f32_e32 v7, 1.0, v7
	v_rcp_f32_e32 v13, v7
	s_nop 0
	v_pk_mul_f32 v[10:11], v[12:13], v[10:11]
	s_nop 0
	v_pk_mul_f32 v[10:11], v[64:65], v[10:11]
	v_pk_mul_f32 v[64:65], v[72:73], v[0:1] op_sel_hi:[1,0]
	v_cvt_pk_bf16_f32 v9, v10, v11
	global_store_dwordx2 v[4:5], v[8:9], off offset:1552
	v_lshlrev_b32_e32 v10, 16, v104
	v_mul_f32_e32 v7, 0xbfb8aa3b, v10
	v_exp_f32_e32 v7, v7
	v_and_b32_e32 v11, 0xffff0000, v104
	v_add_f32_e32 v7, 1.0, v7
	v_rcp_f32_e32 v12, v7
	v_mul_f32_e32 v7, 0xbfb8aa3b, v11
	v_exp_f32_e32 v7, v7
	s_nop 0
	v_add_f32_e32 v7, 1.0, v7
	v_rcp_f32_e32 v13, v7
	s_nop 0
	v_pk_mul_f32 v[10:11], v[12:13], v[10:11]
	s_nop 0
	v_pk_mul_f32 v[10:11], v[64:65], v[10:11]
	v_pk_mul_f32 v[64:65], v[74:75], v[0:1] op_sel_hi:[1,0]
	v_cvt_pk_bf16_f32 v8, v10, v11
	v_lshlrev_b32_e32 v10, 16, v105
	v_mul_f32_e32 v7, 0xbfb8aa3b, v10
	v_exp_f32_e32 v7, v7
	v_and_b32_e32 v11, 0xffff0000, v105
	v_add_f32_e32 v7, 1.0, v7
	v_rcp_f32_e32 v12, v7
	v_mul_f32_e32 v7, 0xbfb8aa3b, v11
	v_exp_f32_e32 v7, v7
	s_nop 0
	v_add_f32_e32 v7, 1.0, v7
	v_rcp_f32_e32 v13, v7
	s_nop 0
	v_pk_mul_f32 v[10:11], v[12:13], v[10:11]
	s_nop 0
	v_pk_mul_f32 v[10:11], v[64:65], v[10:11]
	v_pk_mul_f32 v[64:65], v[76:77], v[0:1] op_sel_hi:[1,0]
	v_cvt_pk_bf16_f32 v9, v10, v11
	global_store_dwordx2 v[4:5], v[8:9], off offset:1568
	v_lshlrev_b32_e32 v10, 16, v106
	v_mul_f32_e32 v7, 0xbfb8aa3b, v10
	v_exp_f32_e32 v7, v7
	v_and_b32_e32 v11, 0xffff0000, v106
	v_add_f32_e32 v7, 1.0, v7
	v_rcp_f32_e32 v12, v7
	v_mul_f32_e32 v7, 0xbfb8aa3b, v11
	v_exp_f32_e32 v7, v7
	s_nop 0
	v_add_f32_e32 v7, 1.0, v7
	v_rcp_f32_e32 v13, v7
	s_nop 0
	v_pk_mul_f32 v[10:11], v[12:13], v[10:11]
	s_nop 0
	v_pk_mul_f32 v[10:11], v[64:65], v[10:11]
	v_pk_mul_f32 v[64:65], v[78:79], v[0:1] op_sel_hi:[1,0]
	v_cvt_pk_bf16_f32 v8, v10, v11
	v_lshlrev_b32_e32 v10, 16, v107
	v_mul_f32_e32 v7, 0xbfb8aa3b, v10
	v_exp_f32_e32 v7, v7
	v_and_b32_e32 v11, 0xffff0000, v107
	v_add_f32_e32 v7, 1.0, v7
	v_rcp_f32_e32 v12, v7
	v_mul_f32_e32 v7, 0xbfb8aa3b, v11
	v_exp_f32_e32 v7, v7
	s_nop 0
	v_add_f32_e32 v7, 1.0, v7
	v_rcp_f32_e32 v13, v7
	s_nop 0
	v_pk_mul_f32 v[10:11], v[12:13], v[10:11]
	s_nop 0
	v_pk_mul_f32 v[10:11], v[64:65], v[10:11]
	s_nop 0
	v_cvt_pk_bf16_f32 v9, v10, v11
	global_store_dwordx2 v[4:5], v[8:9], off offset:1584
	v_lshlrev_b32_e32 v10, 16, v108
	v_mul_f32_e32 v7, 0xbfb8aa3b, v10
	v_exp_f32_e32 v7, v7
	v_and_b32_e32 v11, 0xffff0000, v108
	v_add_f32_e32 v7, 1.0, v7
	v_rcp_f32_e32 v12, v7
	v_mul_f32_e32 v7, 0xbfb8aa3b, v11
	v_exp_f32_e32 v7, v7
	s_nop 0
	v_add_f32_e32 v7, 1.0, v7
	v_rcp_f32_e32 v13, v7
	s_nop 0
	v_pk_mul_f32 v[10:11], v[12:13], v[10:11]
	s_nop 0
	v_pk_mul_f32 v[10:11], v[48:49], v[10:11]
	v_pk_mul_f32 v[48:49], v[50:51], v[0:1] op_sel_hi:[1,0]
	v_cvt_pk_bf16_f32 v8, v10, v11
	v_lshlrev_b32_e32 v10, 16, v109
	v_mul_f32_e32 v7, 0xbfb8aa3b, v10
	v_exp_f32_e32 v7, v7
	v_and_b32_e32 v11, 0xffff0000, v109
	v_add_f32_e32 v7, 1.0, v7
	v_rcp_f32_e32 v12, v7
	v_mul_f32_e32 v7, 0xbfb8aa3b, v11
	v_exp_f32_e32 v7, v7
	s_nop 0
	v_add_f32_e32 v7, 1.0, v7
	v_rcp_f32_e32 v13, v7
	s_nop 0
	v_pk_mul_f32 v[10:11], v[12:13], v[10:11]
	s_nop 0
	v_pk_mul_f32 v[10:11], v[48:49], v[10:11]
	v_pk_mul_f32 v[48:49], v[52:53], v[0:1] op_sel_hi:[1,0]
	v_cvt_pk_bf16_f32 v9, v10, v11
	global_store_dwordx2 v[4:5], v[8:9], off offset:1600
	v_lshlrev_b32_e32 v10, 16, v110
	v_mul_f32_e32 v7, 0xbfb8aa3b, v10
	v_exp_f32_e32 v7, v7
	v_and_b32_e32 v11, 0xffff0000, v110
	v_add_f32_e32 v7, 1.0, v7
	v_rcp_f32_e32 v12, v7
	v_mul_f32_e32 v7, 0xbfb8aa3b, v11
	v_exp_f32_e32 v7, v7
	s_nop 0
	v_add_f32_e32 v7, 1.0, v7
	v_rcp_f32_e32 v13, v7
	s_nop 0
	v_pk_mul_f32 v[10:11], v[12:13], v[10:11]
	s_nop 0
	v_pk_mul_f32 v[10:11], v[48:49], v[10:11]
	v_pk_mul_f32 v[48:49], v[54:55], v[0:1] op_sel_hi:[1,0]
	v_cvt_pk_bf16_f32 v8, v10, v11
	v_lshlrev_b32_e32 v10, 16, v111
	v_mul_f32_e32 v7, 0xbfb8aa3b, v10
; DI unsigned pack2(float a, float b) { f32v2 v = {a, b}; return __builtin_bit_cast(unsigned, __builtin_convertvector(v, bf16v2)); }
; DI float bflo(unsigned v) { return __uint_as_float(v << 16); }
; DI float bfhi(unsigned v) { return __uint_as_float(v & 0xffff0000u); }
; DI float silu(float x) { return x * sigm(x); }
; DI float xhalf_sum(float v) { auto r = __builtin_amdgcn_permlane32_swap(__float_as_uint(v), __float_as_uint(v), false, false); return __uint_as_float(r[0]) + __uint_as_float(r[1]); }
; template <int DK>
; DI void attn_item2(const u16* __restrict__ Q, int ldq, const u16* __restrict__ K, int ldk, const u16* __restrict__ Vt, int nTiles,
;                    u16* __restrict__ Gp, const u16* __restrict__ Zp, char* smem, int tid) {
;     ...
; #pragma unroll
;   for (int qw = 0; qw < 2; qw++) {
;     const float inv = __builtin_amdgcn_rcpf(xhalf_sum(qw ? l_run1 : l_run0));
;     const int q = (w * 2 + qw) * 32 + r;
; #pragma unroll
;     for (int db = 0; db < 2; db++)
; #pragma unroll
;       for (int g = 0; g < 4; g++) {
;         const int d0 = 32 * db + 8 * g + 4 * h;
;         uint2 zz = *(const uint2*)(Zp + (size_t)q * PKW + d0);
;         uint2 ov; ov.x = pack2(o[qw][db][4 * g] * inv * silu(bflo(zz.x)), o[qw][db][4 * g + 1] * inv * silu(bfhi(zz.x)));
;         ov.y = pack2(o[qw][db][4 * g + 2] * inv * silu(bflo(zz.y)), o[qw][db][4 * g + 3] * inv * silu(bfhi(zz.y)));
;         *(uint2*)(Gp + (size_t)q * 1024 + d0) = ov;
;       }
	v_exp_f32_e32 v7, v7
	v_and_b32_e32 v11, 0xffff0000, v111
	v_add_f32_e32 v7, 1.0, v7
	v_rcp_f32_e32 v12, v7
	v_mul_f32_e32 v7, 0xbfb8aa3b, v11
	v_exp_f32_e32 v7, v7
	s_nop 0
	v_add_f32_e32 v7, 1.0, v7
	v_rcp_f32_e32 v13, v7
	s_nop 0
	v_pk_mul_f32 v[10:11], v[12:13], v[10:11]
	s_nop 0
	v_pk_mul_f32 v[10:11], v[48:49], v[10:11]
	v_pk_mul_f32 v[48:49], v[56:57], v[0:1] op_sel_hi:[1,0]
	v_cvt_pk_bf16_f32 v9, v10, v11
	global_store_dwordx2 v[4:5], v[8:9], off offset:1616
	v_lshlrev_b32_e32 v10, 16, v112
	v_mul_f32_e32 v7, 0xbfb8aa3b, v10
	v_exp_f32_e32 v7, v7
	v_and_b32_e32 v11, 0xffff0000, v112
	v_add_f32_e32 v7, 1.0, v7
	v_rcp_f32_e32 v12, v7
	v_mul_f32_e32 v7, 0xbfb8aa3b, v11
	v_exp_f32_e32 v7, v7
	s_nop 0
	v_add_f32_e32 v7, 1.0, v7
	v_rcp_f32_e32 v13, v7
	s_nop 0
	v_pk_mul_f32 v[10:11], v[12:13], v[10:11]
	s_nop 0
	v_pk_mul_f32 v[10:11], v[48:49], v[10:11]
	v_pk_mul_f32 v[48:49], v[58:59], v[0:1] op_sel_hi:[1,0]
	v_cvt_pk_bf16_f32 v8, v10, v11
	v_lshlrev_b32_e32 v10, 16, v113
	v_mul_f32_e32 v7, 0xbfb8aa3b, v10
	v_exp_f32_e32 v7, v7
	v_and_b32_e32 v11, 0xffff0000, v113
	v_add_f32_e32 v7, 1.0, v7
	v_rcp_f32_e32 v12, v7
	v_mul_f32_e32 v7, 0xbfb8aa3b, v11
	v_exp_f32_e32 v7, v7
	s_nop 0
	v_add_f32_e32 v7, 1.0, v7
	v_rcp_f32_e32 v13, v7
	s_nop 0
	v_pk_mul_f32 v[10:11], v[12:13], v[10:11]
	s_nop 0
	v_pk_mul_f32 v[10:11], v[48:49], v[10:11]
	v_pk_mul_f32 v[12:13], v[60:61], v[0:1] op_sel_hi:[1,0]
	v_cvt_pk_bf16_f32 v9, v10, v11
	global_store_dwordx2 v[4:5], v[8:9], off offset:1632
	s_waitcnt vmcnt(1)
	v_lshlrev_b32_e32 v8, 16, v114
	v_and_b32_e32 v9, 0xffff0000, v114
	v_mul_f32_e32 v2, 0xbfb8aa3b, v8
	v_exp_f32_e32 v2, v2
	s_nop 0
	v_add_f32_e32 v2, 1.0, v2
	v_rcp_f32_e32 v10, v2
	v_mul_f32_e32 v2, 0xbfb8aa3b, v9
	v_exp_f32_e32 v2, v2
	s_nop 0
	v_add_f32_e32 v2, 1.0, v2
	v_rcp_f32_e32 v11, v2
	s_nop 0
	v_pk_mul_f32 v[8:9], v[10:11], v[8:9]
	s_nop 0
	v_pk_mul_f32 v[8:9], v[12:13], v[8:9]
	v_pk_mul_f32 v[12:13], v[62:63], v[0:1] op_sel_hi:[1,0]
	v_cvt_pk_bf16_f32 v2, v8, v9
	v_lshlrev_b32_e32 v8, 16, v115
	v_and_b32_e32 v9, 0xffff0000, v115
	v_mul_f32_e32 v3, 0xbfb8aa3b, v8
	v_mul_f32_e32 v0, 0xbfb8aa3b, v9
	v_exp_f32_e32 v3, v3
	v_exp_f32_e32 v0, v0
	v_add_f32_e32 v3, 1.0, v3
	v_add_f32_e32 v0, 1.0, v0
	v_rcp_f32_e32 v10, v3
	v_rcp_f32_e32 v11, v0
	v_mov_b32_e32 v0, v6
	s_nop 1
	v_permlane32_swap_b32_e32 v6, v0
	v_pk_mul_f32 v[8:9], v[10:11], v[8:9]
	v_add_f32_e32 v0, v6, v0
	v_pk_mul_f32 v[8:9], v[12:13], v[8:9]
	v_rcp_f32_e32 v0, v0
	v_cvt_pk_bf16_f32 v3, v8, v9
	global_store_dwordx2 v[4:5], v[2:3], off offset:1648
	v_lshl_add_u64 v[2:3], v[96:97], 0, v[178:179]
	v_lshl_add_u64 v[4:5], v[2:3], 0, v[192:193]
	global_load_dwordx2 v[116:117], v[4:5], off offset:3072
	global_load_dwordx2 v[118:119], v[4:5], off offset:3088
	global_load_dwordx2 v[120:121], v[4:5], off offset:3104
	global_load_dwordx2 v[122:123], v[4:5], off offset:3120
	global_load_dwordx2 v[124:125], v[4:5], off offset:3136
	global_load_dwordx2 v[126:127], v[4:5], off offset:3152
	global_load_dwordx2 v[128:129], v[4:5], off offset:3168
	global_load_dwordx2 v[130:131], v[4:5], off offset:3184
	v_pk_mul_f32 v[12:13], v[32:33], v[0:1] op_sel_hi:[1,0]
	v_lshl_add_u64 v[6:7], v[14:15], 0, v[180:181]
	s_waitcnt vmcnt(0)
	v_lshlrev_b32_e32 v8, 16, v116
	v_and_b32_e32 v9, 0xffff0000, v116
	v_mul_f32_e32 v2, 0xbfb8aa3b, v8
	v_exp_f32_e32 v2, v2
	s_nop 0
	v_add_f32_e32 v2, 1.0, v2
	v_rcp_f32_e32 v10, v2
	v_mul_f32_e32 v2, 0xbfb8aa3b, v9
	v_exp_f32_e32 v2, v2
	s_nop 0
	v_add_f32_e32 v2, 1.0, v2
	v_rcp_f32_e32 v11, v2
	v_lshlrev_b32_e32 v2, 16, v117
	v_and_b32_e32 v3, 0xffff0000, v117
	v_pk_mul_f32 v[8:9], v[10:11], v[8:9]
	s_nop 0
	v_pk_mul_f32 v[8:9], v[12:13], v[8:9]
	v_pk_mul_f32 v[12:13], v[34:35], v[0:1] op_sel_hi:[1,0]
	v_cvt_pk_bf16_f32 v8, v8, v9
	v_mul_f32_e32 v9, 0xbfb8aa3b, v2
	v_exp_f32_e32 v9, v9
	s_nop 0
	v_add_f32_e32 v9, 1.0, v9
	v_rcp_f32_e32 v10, v9
	v_mul_f32_e32 v9, 0xbfb8aa3b, v3
	v_exp_f32_e32 v9, v9
	s_nop 0
	v_add_f32_e32 v9, 1.0, v9
	v_rcp_f32_e32 v11, v9
	s_nop 0
	v_pk_mul_f32 v[2:3], v[10:11], v[2:3]
	s_nop 0
	v_pk_mul_f32 v[2:3], v[12:13], v[2:3]
	v_pk_mul_f32 v[12:13], v[36:37], v[0:1] op_sel_hi:[1,0]
	v_cvt_pk_bf16_f32 v9, v2, v3
	v_lshl_add_u64 v[2:3], v[6:7], 0, v[192:193]
	s_nop 0
	global_store_dwordx2 v[2:3], v[8:9], off offset:1536
	s_waitcnt vmcnt(1)
; DI unsigned pack2(float a, float b) { f32v2 v = {a, b}; return __builtin_bit_cast(unsigned, __builtin_convertvector(v, bf16v2)); }
; DI float bflo(unsigned v) { return __uint_as_float(v << 16); }
; DI float bfhi(unsigned v) { return __uint_as_float(v & 0xffff0000u); }
; DI float silu(float x) { return x * sigm(x); }
; DI float xhalf_sum(float v) { auto r = __builtin_amdgcn_permlane32_swap(__float_as_uint(v), __float_as_uint(v), false, false); return __uint_as_float(r[0]) + __uint_as_float(r[1]); }
; template <int DK>
; DI void attn_item2(const u16* __restrict__ Q, int ldq, const u16* __restrict__ K, int ldk, const u16* __restrict__ Vt, int nTiles,
;                    u16* __restrict__ Gp, const u16* __restrict__ Zp, char* smem, int tid) {
;     ...
; #pragma unroll
;   for (int qw = 0; qw < 2; qw++) {
;     const float inv = __builtin_amdgcn_rcpf(xhalf_sum(qw ? l_run1 : l_run0));
;     const int q = (w * 2 + qw) * 32 + r;
; #pragma unroll
;     for (int db = 0; db < 2; db++)
; #pragma unroll
;       for (int g = 0; g < 4; g++) {
;         const int d0 = 32 * db + 8 * g + 4 * h;
;         uint2 zz = *(const uint2*)(Zp + (size_t)q * PKW + d0);
;         uint2 ov; ov.x = pack2(o[qw][db][4 * g] * inv * silu(bflo(zz.x)), o[qw][db][4 * g + 1] * inv * silu(bfhi(zz.x)));
;         ov.y = pack2(o[qw][db][4 * g + 2] * inv * silu(bflo(zz.y)), o[qw][db][4 * g + 3] * inv * silu(bfhi(zz.y)));
;         *(uint2*)(Gp + (size_t)q * 1024 + d0) = ov;
;       }
	v_lshlrev_b32_e32 v8, 16, v118
	v_and_b32_e32 v9, 0xffff0000, v118
	v_mul_f32_e32 v6, 0xbfb8aa3b, v8
	v_exp_f32_e32 v6, v6
	s_nop 0
	v_add_f32_e32 v6, 1.0, v6
	v_rcp_f32_e32 v10, v6
	v_mul_f32_e32 v6, 0xbfb8aa3b, v9
	v_exp_f32_e32 v6, v6
	s_nop 0
	v_add_f32_e32 v6, 1.0, v6
	v_rcp_f32_e32 v11, v6
	s_nop 0
	v_pk_mul_f32 v[8:9], v[10:11], v[8:9]
	s_nop 0
	v_pk_mul_f32 v[8:9], v[12:13], v[8:9]
	v_pk_mul_f32 v[12:13], v[38:39], v[0:1] op_sel_hi:[1,0]
	v_cvt_pk_bf16_f32 v6, v8, v9
	v_lshlrev_b32_e32 v8, 16, v119
	v_and_b32_e32 v9, 0xffff0000, v119
	v_mul_f32_e32 v7, 0xbfb8aa3b, v8
	v_exp_f32_e32 v7, v7
	s_nop 0
	v_add_f32_e32 v7, 1.0, v7
	v_rcp_f32_e32 v10, v7
	v_mul_f32_e32 v7, 0xbfb8aa3b, v9
	v_exp_f32_e32 v7, v7
	s_nop 0
	v_add_f32_e32 v7, 1.0, v7
	v_rcp_f32_e32 v11, v7
	s_nop 0
	v_pk_mul_f32 v[8:9], v[10:11], v[8:9]
	s_nop 0
	v_pk_mul_f32 v[8:9], v[12:13], v[8:9]
	v_pk_mul_f32 v[12:13], v[40:41], v[0:1] op_sel_hi:[1,0]
	v_cvt_pk_bf16_f32 v7, v8, v9
	global_store_dwordx2 v[2:3], v[6:7], off offset:1552
	v_lshlrev_b32_e32 v8, 16, v120
	v_and_b32_e32 v9, 0xffff0000, v120
	v_mul_f32_e32 v6, 0xbfb8aa3b, v8
	v_exp_f32_e32 v6, v6
	s_nop 0
	v_add_f32_e32 v6, 1.0, v6
	v_rcp_f32_e32 v10, v6
	v_mul_f32_e32 v6, 0xbfb8aa3b, v9
	v_exp_f32_e32 v6, v6
	s_nop 0
	v_add_f32_e32 v6, 1.0, v6
	v_rcp_f32_e32 v11, v6
	s_nop 0
	v_pk_mul_f32 v[8:9], v[10:11], v[8:9]
	s_nop 0
	v_pk_mul_f32 v[8:9], v[12:13], v[8:9]
	v_pk_mul_f32 v[12:13], v[42:43], v[0:1] op_sel_hi:[1,0]
	v_cvt_pk_bf16_f32 v6, v8, v9
	v_lshlrev_b32_e32 v8, 16, v121
	v_and_b32_e32 v9, 0xffff0000, v121
	v_mul_f32_e32 v7, 0xbfb8aa3b, v8
	v_exp_f32_e32 v7, v7
	s_nop 0
	v_add_f32_e32 v7, 1.0, v7
	v_rcp_f32_e32 v10, v7
	v_mul_f32_e32 v7, 0xbfb8aa3b, v9
	v_exp_f32_e32 v7, v7
	s_nop 0
	v_add_f32_e32 v7, 1.0, v7
	v_rcp_f32_e32 v11, v7
	s_nop 0
	v_pk_mul_f32 v[8:9], v[10:11], v[8:9]
	s_nop 0
	v_pk_mul_f32 v[8:9], v[12:13], v[8:9]
	v_pk_mul_f32 v[12:13], v[44:45], v[0:1] op_sel_hi:[1,0]
	v_cvt_pk_bf16_f32 v7, v8, v9
	global_store_dwordx2 v[2:3], v[6:7], off offset:1568
	v_lshlrev_b32_e32 v8, 16, v122
	v_and_b32_e32 v9, 0xffff0000, v122
	v_mul_f32_e32 v6, 0xbfb8aa3b, v8
	v_exp_f32_e32 v6, v6
	s_nop 0
	v_add_f32_e32 v6, 1.0, v6
	v_rcp_f32_e32 v10, v6
	v_mul_f32_e32 v6, 0xbfb8aa3b, v9
	v_exp_f32_e32 v6, v6
	s_nop 0
	v_add_f32_e32 v6, 1.0, v6
	v_rcp_f32_e32 v11, v6
	s_nop 0
	v_pk_mul_f32 v[8:9], v[10:11], v[8:9]
	s_nop 0
	v_pk_mul_f32 v[8:9], v[12:13], v[8:9]
	v_pk_mul_f32 v[12:13], v[46:47], v[0:1] op_sel_hi:[1,0]
	v_cvt_pk_bf16_f32 v6, v8, v9
	v_lshlrev_b32_e32 v8, 16, v123
	v_and_b32_e32 v9, 0xffff0000, v123
	v_mul_f32_e32 v7, 0xbfb8aa3b, v8
	v_exp_f32_e32 v7, v7
	s_nop 0
	v_add_f32_e32 v7, 1.0, v7
	v_rcp_f32_e32 v10, v7
	v_mul_f32_e32 v7, 0xbfb8aa3b, v9
	v_exp_f32_e32 v7, v7
	s_nop 0
	v_add_f32_e32 v7, 1.0, v7
	v_rcp_f32_e32 v11, v7
	s_nop 0
	v_pk_mul_f32 v[8:9], v[10:11], v[8:9]
	s_nop 0
	v_pk_mul_f32 v[8:9], v[12:13], v[8:9]
	v_pk_mul_f32 v[12:13], v[16:17], v[0:1] op_sel_hi:[1,0]
	v_cvt_pk_bf16_f32 v7, v8, v9
	global_store_dwordx2 v[2:3], v[6:7], off offset:1584
	v_lshlrev_b32_e32 v8, 16, v124
	v_and_b32_e32 v9, 0xffff0000, v124
	v_mul_f32_e32 v6, 0xbfb8aa3b, v8
	v_exp_f32_e32 v6, v6
	s_nop 0
	v_add_f32_e32 v6, 1.0, v6
	v_rcp_f32_e32 v10, v6
	v_mul_f32_e32 v6, 0xbfb8aa3b, v9
	v_exp_f32_e32 v6, v6
	s_nop 0
	v_add_f32_e32 v6, 1.0, v6
	v_rcp_f32_e32 v11, v6
	s_nop 0
	v_pk_mul_f32 v[8:9], v[10:11], v[8:9]
	s_nop 0
	v_pk_mul_f32 v[8:9], v[12:13], v[8:9]
	v_pk_mul_f32 v[12:13], v[18:19], v[0:1] op_sel_hi:[1,0]
	v_cvt_pk_bf16_f32 v6, v8, v9
	v_lshlrev_b32_e32 v8, 16, v125
	v_and_b32_e32 v9, 0xffff0000, v125
	v_mul_f32_e32 v7, 0xbfb8aa3b, v8
	v_exp_f32_e32 v7, v7
	s_nop 0
	v_add_f32_e32 v7, 1.0, v7
	v_rcp_f32_e32 v10, v7
	v_mul_f32_e32 v7, 0xbfb8aa3b, v9
	v_exp_f32_e32 v7, v7
	s_nop 0
	v_add_f32_e32 v7, 1.0, v7
	v_rcp_f32_e32 v11, v7
	s_nop 0
	v_pk_mul_f32 v[8:9], v[10:11], v[8:9]
	s_nop 0
	v_pk_mul_f32 v[8:9], v[12:13], v[8:9]
	v_pk_mul_f32 v[12:13], v[20:21], v[0:1] op_sel_hi:[1,0]
	v_cvt_pk_bf16_f32 v7, v8, v9
	global_store_dwordx2 v[2:3], v[6:7], off offset:1600
	v_lshlrev_b32_e32 v8, 16, v126
	v_and_b32_e32 v9, 0xffff0000, v126
	v_mul_f32_e32 v6, 0xbfb8aa3b, v8
	v_exp_f32_e32 v6, v6
	s_nop 0
	v_add_f32_e32 v6, 1.0, v6
	v_rcp_f32_e32 v10, v6
	v_mul_f32_e32 v6, 0xbfb8aa3b, v9
	v_exp_f32_e32 v6, v6
	s_nop 0
	v_add_f32_e32 v6, 1.0, v6
	v_rcp_f32_e32 v11, v6
	s_nop 0
	v_pk_mul_f32 v[8:9], v[10:11], v[8:9]
	s_nop 0
	v_pk_mul_f32 v[8:9], v[12:13], v[8:9]
	v_pk_mul_f32 v[12:13], v[22:23], v[0:1] op_sel_hi:[1,0]
	v_cvt_pk_bf16_f32 v6, v8, v9
	v_lshlrev_b32_e32 v8, 16, v127
	v_and_b32_e32 v9, 0xffff0000, v127
	v_mul_f32_e32 v7, 0xbfb8aa3b, v8
	v_exp_f32_e32 v7, v7
	s_nop 0
	v_add_f32_e32 v7, 1.0, v7
	v_rcp_f32_e32 v10, v7
	v_mul_f32_e32 v7, 0xbfb8aa3b, v9
	v_exp_f32_e32 v7, v7
	s_nop 0
	v_add_f32_e32 v7, 1.0, v7
	v_rcp_f32_e32 v11, v7
	s_nop 0
	v_pk_mul_f32 v[8:9], v[10:11], v[8:9]
	s_nop 0
	v_pk_mul_f32 v[8:9], v[12:13], v[8:9]
	v_pk_mul_f32 v[12:13], v[24:25], v[0:1] op_sel_hi:[1,0]
	v_cvt_pk_bf16_f32 v7, v8, v9
	global_store_dwordx2 v[2:3], v[6:7], off offset:1616
	v_lshlrev_b32_e32 v8, 16, v128
	v_and_b32_e32 v9, 0xffff0000, v128
	v_mul_f32_e32 v6, 0xbfb8aa3b, v8
	v_exp_f32_e32 v6, v6
	s_nop 0
	v_add_f32_e32 v6, 1.0, v6
	v_rcp_f32_e32 v10, v6
	v_mul_f32_e32 v6, 0xbfb8aa3b, v9
	v_exp_f32_e32 v6, v6
	s_nop 0
	v_add_f32_e32 v6, 1.0, v6
	v_rcp_f32_e32 v11, v6
	s_nop 0
	v_pk_mul_f32 v[8:9], v[10:11], v[8:9]
	s_nop 0
	v_pk_mul_f32 v[8:9], v[12:13], v[8:9]
	v_pk_mul_f32 v[12:13], v[26:27], v[0:1] op_sel_hi:[1,0]
	v_cvt_pk_bf16_f32 v6, v8, v9
	v_lshlrev_b32_e32 v8, 16, v129
	v_and_b32_e32 v9, 0xffff0000, v129
	v_mul_f32_e32 v7, 0xbfb8aa3b, v8
	v_exp_f32_e32 v7, v7
	s_nop 0
	v_add_f32_e32 v7, 1.0, v7
	v_rcp_f32_e32 v10, v7
	v_mul_f32_e32 v7, 0xbfb8aa3b, v9
	v_exp_f32_e32 v7, v7
	s_nop 0
	v_add_f32_e32 v7, 1.0, v7
	v_rcp_f32_e32 v11, v7
	s_nop 0
	v_pk_mul_f32 v[8:9], v[10:11], v[8:9]
	s_nop 0
	v_pk_mul_f32 v[8:9], v[12:13], v[8:9]
	v_pk_mul_f32 v[10:11], v[28:29], v[0:1] op_sel_hi:[1,0]
	v_cvt_pk_bf16_f32 v7, v8, v9
	global_store_dwordx2 v[2:3], v[6:7], off offset:1632
	s_waitcnt vmcnt(1)
; DI unsigned pack2(float a, float b) { f32v2 v = {a, b}; return __builtin_bit_cast(unsigned, __builtin_convertvector(v, bf16v2)); }
; DI float bflo(unsigned v) { return __uint_as_float(v << 16); }
; DI float bfhi(unsigned v) { return __uint_as_float(v & 0xffff0000u); }
; DI float silu(float x) { return x * sigm(x); }
; template <int DK>
; DI void attn_item2(const u16* __restrict__ Q, int ldq, const u16* __restrict__ K, int ldk, const u16* __restrict__ Vt, int nTiles,
;                    u16* __restrict__ Gp, const u16* __restrict__ Zp, char* smem, int tid) {
;     ...
; #pragma unroll
;     for (int db = 0; db < 2; db++)
; #pragma unroll
;       for (int g = 0; g < 4; g++) {
;         const int d0 = 32 * db + 8 * g + 4 * h;
;         uint2 zz = *(const uint2*)(Zp + (size_t)q * PKW + d0);
;         uint2 ov; ov.x = pack2(o[qw][db][4 * g] * inv * silu(bflo(zz.x)), o[qw][db][4 * g + 1] * inv * silu(bfhi(zz.x)));
;         ov.y = pack2(o[qw][db][4 * g + 2] * inv * silu(bflo(zz.y)), o[qw][db][4 * g + 3] * inv * silu(bfhi(zz.y)));
;         *(uint2*)(Gp + (size_t)q * 1024 + d0) = ov;
;       }
; DI int fetch_item(unsigned* ctr, char* smem) {
;   volatile int* slot = (volatile int*)(smem + SMEM_BYTES - 16);
;   __syncthreads();
;   if (threadIdx.x == 0) *slot = (int)__hip_atomic_fetch_add(ctr, 1u, __ATOMIC_RELAXED, __HIP_MEMORY_SCOPE_AGENT);
;   __syncthreads();
;   return *slot;
; }
	v_lshlrev_b32_e32 v6, 16, v130
	v_and_b32_e32 v7, 0xffff0000, v130
	v_mul_f32_e32 v4, 0xbfb8aa3b, v6
	v_exp_f32_e32 v4, v4
	s_nop 0
	v_add_f32_e32 v4, 1.0, v4
	v_rcp_f32_e32 v8, v4
	v_mul_f32_e32 v4, 0xbfb8aa3b, v7
	v_exp_f32_e32 v4, v4
	s_nop 0
	v_add_f32_e32 v4, 1.0, v4
	v_rcp_f32_e32 v9, v4
	s_nop 0
	v_pk_mul_f32 v[6:7], v[8:9], v[6:7]
	s_nop 0
	v_pk_mul_f32 v[6:7], v[10:11], v[6:7]
	v_pk_mul_f32 v[10:11], v[30:31], v[0:1] op_sel_hi:[1,0]
	v_cvt_pk_bf16_f32 v4, v6, v7
	v_lshlrev_b32_e32 v6, 16, v131
	v_and_b32_e32 v7, 0xffff0000, v131
	v_mul_f32_e32 v5, 0xbfb8aa3b, v6
	v_mul_f32_e32 v0, 0xbfb8aa3b, v7
	v_exp_f32_e32 v5, v5
	v_exp_f32_e32 v0, v0
	v_add_f32_e32 v5, 1.0, v5
	v_add_f32_e32 v0, 1.0, v0
	v_rcp_f32_e32 v8, v5
	v_rcp_f32_e32 v9, v0
	s_nop 0
	v_pk_mul_f32 v[6:7], v[8:9], v[6:7]
	s_nop 0
	v_pk_mul_f32 v[6:7], v[10:11], v[6:7]
	s_nop 0
	v_cvt_pk_bf16_f32 v5, v6, v7
	global_store_dwordx2 v[2:3], v[4:5], off offset:1648
	s_barrier
	s_and_saveexec_b64 s[6:7], s[92:93]
	s_cbranch_execz .LBB0_855
	s_mov_b64 s[8:9], exec
	v_mbcnt_lo_u32_b32 v0, s8, 0
	v_mbcnt_hi_u32_b32 v0, s9, v0
	v_cmp_eq_u32_e32 vcc, 0, v0
	s_and_saveexec_b64 s[2:3], vcc
	s_cbranch_execz .LBB0_854
	s_bcnt1_i32_b64 s8, s[8:9]
	v_mov_b32_e32 v2, s8
	v_readlane_b32 s8, v254, 51
	v_readlane_b32 s9, v254, 52
	s_nop 4
	global_atomic_add v2, v1, v2, s[8:9] sc0
	s_branch .LBB0_854

; DI unsigned pack2(float a, float b) { f32v2 v = {a, b}; return __builtin_bit_cast(unsigned, __builtin_convertvector(v, bf16v2)); }
; DI float bflo(unsigned v) { return __uint_as_float(v << 16); }
; DI float bfhi(unsigned v) { return __uint_as_float(v & 0xffff0000u); }
; DI float silu(float x) { return x * sigm(x); }
; DI float xhalf_sum(float v) { auto r = __builtin_amdgcn_permlane32_swap(__float_as_uint(v), __float_as_uint(v), false, false); return __uint_as_float(r[0]) + __uint_as_float(r[1]); }
; template <int DK, bool NA> ...
;     ...
;   const float lt = xhalf_sum(l_run);
;   const float inv = __builtin_amdgcn_rcpf(lt);
;   const int q = w * 32 + r;
; #pragma unroll
;   for (int db = 0; db < 2; db++)
; #pragma unroll
;     for (int g = 0; g < 4; g++) {
;       const int d0 = 32 * db + 8 * g + 4 * h;
;       uint2 zz = *(const uint2*)(Zp + (size_t)q * PKW + d0);
;       uint2 ov; ov.x = pack2(o[db][4 * g] * inv * silu(bflo(zz.x)), o[db][4 * g + 1] * inv * silu(bfhi(zz.x)));
;       ov.y = pack2(o[db][4 * g + 2] * inv * silu(bflo(zz.y)), o[db][4 * g + 3] * inv * silu(bfhi(zz.y)));
;       *(uint2*)(Gp + (size_t)q * 1024 + d0) = ov;
;     }
.LBB0_1004:
	s_or_b64 exec, exec, s[88:89]
	v_readlane_b32 s0, v253, 48
	v_lshlrev_b64 v[34:35], 11, v[120:121]
	v_readlane_b32 s1, v253, 49
	v_mov_b32_e32 v123, v1
	v_mov_b32_e32 v117, v1
	v_lshl_add_u64 v[34:35], s[0:1], 0, v[34:35]
	v_lshl_add_u64 v[34:35], v[34:35], 0, v[122:123]
	v_lshl_add_u64 v[36:37], v[34:35], 0, v[110:111]
	v_lshl_add_u64 v[34:35], v[118:119], 0, v[116:117]
	global_load_dwordx2 v[44:45], v[34:35], off offset:1536
	global_load_dwordx2 v[46:47], v[34:35], off offset:1552
	global_load_dwordx2 v[48:49], v[34:35], off offset:1568
	global_load_dwordx2 v[50:51], v[34:35], off offset:1584
	global_load_dwordx2 v[52:53], v[34:35], off offset:1600
	global_load_dwordx2 v[54:55], v[34:35], off offset:1616
	global_load_dwordx2 v[56:57], v[34:35], off offset:1632
	global_load_dwordx2 v[58:59], v[34:35], off offset:1648
	v_mov_b32_e32 v0, v133
	s_nop 1
	v_permlane32_swap_b32_e32 v133, v0
	v_add_f32_e32 v0, v133, v0
	v_rcp_f32_e32 v0, v0
	s_waitcnt vmcnt(0)
	v_lshlrev_b32_e32 v40, 16, v44
	v_and_b32_e32 v41, 0xffff0000, v44
	v_mul_f32_e32 v38, 0xbfb8aa3b, v40
	v_exp_f32_e32 v38, v38
	v_pk_mul_f32 v[18:19], v[18:19], v[0:1] op_sel_hi:[1,0]
	v_pk_mul_f32 v[20:21], v[20:21], v[0:1] op_sel_hi:[1,0]
	v_pk_mul_f32 v[22:23], v[22:23], v[0:1] op_sel_hi:[1,0]
	v_add_f32_e32 v38, 1.0, v38
	v_rcp_f32_e32 v42, v38
	v_mul_f32_e32 v38, 0xbfb8aa3b, v41
	v_exp_f32_e32 v38, v38
	v_pk_mul_f32 v[24:25], v[24:25], v[0:1] op_sel_hi:[1,0]
	v_pk_mul_f32 v[26:27], v[26:27], v[0:1] op_sel_hi:[1,0]
	v_pk_mul_f32 v[2:3], v[2:3], v[0:1] op_sel_hi:[1,0]
	v_add_f32_e32 v38, 1.0, v38
	v_rcp_f32_e32 v43, v38
	v_pk_mul_f32 v[4:5], v[4:5], v[0:1] op_sel_hi:[1,0]
	v_pk_mul_f32 v[6:7], v[6:7], v[0:1] op_sel_hi:[1,0]
	v_pk_mul_f32 v[8:9], v[8:9], v[0:1] op_sel_hi:[1,0]
	v_pk_mul_f32 v[40:41], v[42:43], v[40:41]
	s_nop 0
	v_pk_mul_f32 v[18:19], v[18:19], v[40:41]
	s_nop 0
	v_cvt_pk_bf16_f32 v38, v18, v19
	v_lshlrev_b32_e32 v18, 16, v45
	v_and_b32_e32 v19, 0xffff0000, v45
	v_mul_f32_e32 v39, 0xbfb8aa3b, v18
	v_exp_f32_e32 v39, v39
	s_nop 0
	v_add_f32_e32 v39, 1.0, v39
	v_rcp_f32_e32 v40, v39
	v_mul_f32_e32 v39, 0xbfb8aa3b, v19
	v_exp_f32_e32 v39, v39
	s_nop 0
	v_add_f32_e32 v39, 1.0, v39
	v_rcp_f32_e32 v41, v39
	s_nop 0
	v_pk_mul_f32 v[18:19], v[40:41], v[18:19]
	s_nop 0
	v_pk_mul_f32 v[18:19], v[20:21], v[18:19]
	v_cvt_pk_bf16_f32 v39, v18, v19
	v_lshl_add_u64 v[18:19], v[36:37], 0, v[116:117]
	global_store_dwordx2 v[18:19], v[38:39], off
	s_waitcnt vmcnt(1)
	v_lshlrev_b32_e32 v36, 16, v46
	v_and_b32_e32 v37, 0xffff0000, v46
	v_mul_f32_e32 v20, 0xbfb8aa3b, v36
	v_exp_f32_e32 v20, v20
	s_nop 0
	v_add_f32_e32 v20, 1.0, v20
	v_rcp_f32_e32 v38, v20
	v_mul_f32_e32 v20, 0xbfb8aa3b, v37
	v_exp_f32_e32 v20, v20
	s_nop 0
	v_add_f32_e32 v20, 1.0, v20
	v_rcp_f32_e32 v39, v20
	s_nop 0
	v_pk_mul_f32 v[36:37], v[38:39], v[36:37]
	s_nop 0
	v_pk_mul_f32 v[22:23], v[22:23], v[36:37]
	s_nop 0
	v_cvt_pk_bf16_f32 v20, v22, v23
	v_lshlrev_b32_e32 v22, 16, v47
	v_and_b32_e32 v23, 0xffff0000, v47
	v_mul_f32_e32 v21, 0xbfb8aa3b, v22
	v_exp_f32_e32 v21, v21
	s_nop 0
	v_add_f32_e32 v21, 1.0, v21
	v_rcp_f32_e32 v36, v21
	v_mul_f32_e32 v21, 0xbfb8aa3b, v23
	v_exp_f32_e32 v21, v21
	s_nop 0
	v_add_f32_e32 v21, 1.0, v21
	v_rcp_f32_e32 v37, v21
	s_nop 0
	v_pk_mul_f32 v[22:23], v[36:37], v[22:23]
	s_nop 0
	v_pk_mul_f32 v[22:23], v[24:25], v[22:23]
	s_nop 0
	v_cvt_pk_bf16_f32 v21, v22, v23
	global_store_dwordx2 v[18:19], v[20:21], off offset:16
	v_lshlrev_b32_e32 v22, 16, v48
	v_and_b32_e32 v23, 0xffff0000, v48
	v_mul_f32_e32 v20, 0xbfb8aa3b, v22
	v_exp_f32_e32 v20, v20
	s_nop 0
	v_add_f32_e32 v20, 1.0, v20
	v_rcp_f32_e32 v24, v20
	v_mul_f32_e32 v20, 0xbfb8aa3b, v23
	v_exp_f32_e32 v20, v20
	s_nop 0
	v_add_f32_e32 v20, 1.0, v20
	v_rcp_f32_e32 v25, v20
	s_nop 0
	v_pk_mul_f32 v[22:23], v[24:25], v[22:23]
	s_nop 0
	v_pk_mul_f32 v[22:23], v[26:27], v[22:23]
	v_pk_mul_f32 v[26:27], v[28:29], v[0:1] op_sel_hi:[1,0]
	v_cvt_pk_bf16_f32 v20, v22, v23
	v_lshlrev_b32_e32 v22, 16, v49
	v_and_b32_e32 v23, 0xffff0000, v49
	v_mul_f32_e32 v21, 0xbfb8aa3b, v22
	v_exp_f32_e32 v21, v21
	s_nop 0
	v_add_f32_e32 v21, 1.0, v21
	v_rcp_f32_e32 v24, v21
	v_mul_f32_e32 v21, 0xbfb8aa3b, v23
	v_exp_f32_e32 v21, v21
	s_nop 0
	v_add_f32_e32 v21, 1.0, v21
	v_rcp_f32_e32 v25, v21
	s_nop 0
	v_pk_mul_f32 v[22:23], v[24:25], v[22:23]
	s_nop 0
	v_pk_mul_f32 v[22:23], v[26:27], v[22:23]
	v_pk_mul_f32 v[26:27], v[30:31], v[0:1] op_sel_hi:[1,0]
	v_cvt_pk_bf16_f32 v21, v22, v23
	global_store_dwordx2 v[18:19], v[20:21], off offset:32
	v_lshlrev_b32_e32 v22, 16, v50
	v_and_b32_e32 v23, 0xffff0000, v50
	v_mul_f32_e32 v20, 0xbfb8aa3b, v22
	v_exp_f32_e32 v20, v20
	s_nop 0
	v_add_f32_e32 v20, 1.0, v20
	v_rcp_f32_e32 v24, v20
	v_mul_f32_e32 v20, 0xbfb8aa3b, v23
	v_exp_f32_e32 v20, v20
	s_nop 0
	v_add_f32_e32 v20, 1.0, v20
	v_rcp_f32_e32 v25, v20
	s_nop 0
	v_pk_mul_f32 v[22:23], v[24:25], v[22:23]
	s_nop 0
; DI unsigned pack2(float a, float b) { f32v2 v = {a, b}; return __builtin_bit_cast(unsigned, __builtin_convertvector(v, bf16v2)); }
; DI float bflo(unsigned v) { return __uint_as_float(v << 16); }
; DI float bfhi(unsigned v) { return __uint_as_float(v & 0xffff0000u); }
; DI float silu(float x) { return x * sigm(x); }
; DI float xhalf_sum(float v) { auto r = __builtin_amdgcn_permlane32_swap(__float_as_uint(v), __float_as_uint(v), false, false); return __uint_as_float(r[0]) + __uint_as_float(r[1]); }
; template <int DK, bool NA> ...
;     ...
;   const float lt = xhalf_sum(l_run);
;   const float inv = __builtin_amdgcn_rcpf(lt);
;   const int q = w * 32 + r;
; #pragma unroll
;   for (int db = 0; db < 2; db++)
; #pragma unroll
;     for (int g = 0; g < 4; g++) {
;       const int d0 = 32 * db + 8 * g + 4 * h;
;       uint2 zz = *(const uint2*)(Zp + (size_t)q * PKW + d0);
;       uint2 ov; ov.x = pack2(o[db][4 * g] * inv * silu(bflo(zz.x)), o[db][4 * g + 1] * inv * silu(bfhi(zz.x)));
;       ov.y = pack2(o[db][4 * g + 2] * inv * silu(bflo(zz.y)), o[db][4 * g + 3] * inv * silu(bfhi(zz.y)));
;       *(uint2*)(Gp + (size_t)q * 1024 + d0) = ov;
;     }
; DI int fetch_item(unsigned* ctr, char* smem) {
;   volatile int* slot = (volatile int*)(smem + SMEM_BYTES - 16);
;   __syncthreads();
;   if (threadIdx.x == 0) *slot = (int)__hip_atomic_fetch_add(ctr, 1u, __ATOMIC_RELAXED, __HIP_MEMORY_SCOPE_AGENT);
;   __syncthreads();
;   return *slot;
; }
	v_pk_mul_f32 v[22:23], v[26:27], v[22:23]
	v_pk_mul_f32 v[26:27], v[32:33], v[0:1] op_sel_hi:[1,0]
	v_cvt_pk_bf16_f32 v20, v22, v23
	v_lshlrev_b32_e32 v22, 16, v51
	v_and_b32_e32 v23, 0xffff0000, v51
	v_mul_f32_e32 v21, 0xbfb8aa3b, v22
	v_exp_f32_e32 v21, v21
	s_nop 0
	v_add_f32_e32 v21, 1.0, v21
	v_rcp_f32_e32 v24, v21
	v_mul_f32_e32 v21, 0xbfb8aa3b, v23
	v_exp_f32_e32 v21, v21
	s_nop 0
	v_add_f32_e32 v21, 1.0, v21
	v_rcp_f32_e32 v25, v21
	s_nop 0
	v_pk_mul_f32 v[22:23], v[24:25], v[22:23]
	s_nop 0
	v_pk_mul_f32 v[22:23], v[26:27], v[22:23]
	s_nop 0
	v_cvt_pk_bf16_f32 v21, v22, v23
	global_store_dwordx2 v[18:19], v[20:21], off offset:48
	v_lshlrev_b32_e32 v22, 16, v52
	v_and_b32_e32 v23, 0xffff0000, v52
	v_mul_f32_e32 v20, 0xbfb8aa3b, v22
	v_exp_f32_e32 v20, v20
	s_nop 0
	v_add_f32_e32 v20, 1.0, v20
	v_rcp_f32_e32 v24, v20
	v_mul_f32_e32 v20, 0xbfb8aa3b, v23
	v_exp_f32_e32 v20, v20
	s_nop 0
	v_add_f32_e32 v20, 1.0, v20
	v_rcp_f32_e32 v25, v20
	v_lshlrev_b32_e32 v20, 16, v53
	v_and_b32_e32 v21, 0xffff0000, v53
	v_pk_mul_f32 v[22:23], v[24:25], v[22:23]
	s_nop 0
	v_pk_mul_f32 v[2:3], v[2:3], v[22:23]
	s_nop 0
	v_cvt_pk_bf16_f32 v2, v2, v3
	v_mul_f32_e32 v3, 0xbfb8aa3b, v20
	v_exp_f32_e32 v3, v3
	s_nop 0
	v_add_f32_e32 v3, 1.0, v3
	v_rcp_f32_e32 v22, v3
	v_mul_f32_e32 v3, 0xbfb8aa3b, v21
	v_exp_f32_e32 v3, v3
	s_nop 0
	v_add_f32_e32 v3, 1.0, v3
	v_rcp_f32_e32 v23, v3
	s_nop 0
	v_pk_mul_f32 v[20:21], v[22:23], v[20:21]
	s_nop 0
	v_pk_mul_f32 v[4:5], v[4:5], v[20:21]
	s_nop 0
	v_cvt_pk_bf16_f32 v3, v4, v5
	global_store_dwordx2 v[18:19], v[2:3], off offset:64
	v_lshlrev_b32_e32 v4, 16, v54
	v_and_b32_e32 v5, 0xffff0000, v54
	v_mul_f32_e32 v2, 0xbfb8aa3b, v4
	v_exp_f32_e32 v2, v2
	s_nop 0
	v_add_f32_e32 v2, 1.0, v2
	v_rcp_f32_e32 v20, v2
	v_mul_f32_e32 v2, 0xbfb8aa3b, v5
	v_exp_f32_e32 v2, v2
	s_nop 0
	v_add_f32_e32 v2, 1.0, v2
	v_rcp_f32_e32 v21, v2
	s_nop 0
	v_pk_mul_f32 v[4:5], v[20:21], v[4:5]
	s_nop 0
	v_pk_mul_f32 v[4:5], v[6:7], v[4:5]
	s_nop 0
	v_cvt_pk_bf16_f32 v2, v4, v5
	v_lshlrev_b32_e32 v4, 16, v55
	v_and_b32_e32 v5, 0xffff0000, v55
	v_mul_f32_e32 v3, 0xbfb8aa3b, v4
	v_exp_f32_e32 v3, v3
	s_nop 0
	v_add_f32_e32 v3, 1.0, v3
	v_rcp_f32_e32 v6, v3
	v_mul_f32_e32 v3, 0xbfb8aa3b, v5
	v_exp_f32_e32 v3, v3
	s_nop 0
	v_add_f32_e32 v3, 1.0, v3
	v_rcp_f32_e32 v7, v3
	s_nop 0
	v_pk_mul_f32 v[4:5], v[6:7], v[4:5]
	s_nop 0
	v_pk_mul_f32 v[4:5], v[8:9], v[4:5]
	v_pk_mul_f32 v[8:9], v[10:11], v[0:1] op_sel_hi:[1,0]
	v_cvt_pk_bf16_f32 v3, v4, v5
	global_store_dwordx2 v[18:19], v[2:3], off offset:80
	v_lshlrev_b32_e32 v4, 16, v56
	v_and_b32_e32 v5, 0xffff0000, v56
	v_mul_f32_e32 v2, 0xbfb8aa3b, v4
	v_exp_f32_e32 v2, v2
	s_nop 0
	v_add_f32_e32 v2, 1.0, v2
	v_rcp_f32_e32 v6, v2
	v_mul_f32_e32 v2, 0xbfb8aa3b, v5
	v_exp_f32_e32 v2, v2
	s_nop 0
	v_add_f32_e32 v2, 1.0, v2
	v_rcp_f32_e32 v7, v2
	s_nop 0
	v_pk_mul_f32 v[4:5], v[6:7], v[4:5]
	s_nop 0
	v_pk_mul_f32 v[4:5], v[8:9], v[4:5]
	v_pk_mul_f32 v[8:9], v[12:13], v[0:1] op_sel_hi:[1,0]
	v_cvt_pk_bf16_f32 v2, v4, v5
	v_lshlrev_b32_e32 v4, 16, v57
	v_and_b32_e32 v5, 0xffff0000, v57
	v_mul_f32_e32 v3, 0xbfb8aa3b, v4
	v_exp_f32_e32 v3, v3
	s_nop 0
	v_add_f32_e32 v3, 1.0, v3
	v_rcp_f32_e32 v6, v3
	v_mul_f32_e32 v3, 0xbfb8aa3b, v5
	v_exp_f32_e32 v3, v3
	s_nop 0
	v_add_f32_e32 v3, 1.0, v3
	v_rcp_f32_e32 v7, v3
	s_nop 0
	v_pk_mul_f32 v[4:5], v[6:7], v[4:5]
	s_nop 0
	v_pk_mul_f32 v[4:5], v[8:9], v[4:5]
	v_pk_mul_f32 v[8:9], v[14:15], v[0:1] op_sel_hi:[1,0]
	v_cvt_pk_bf16_f32 v3, v4, v5
	global_store_dwordx2 v[18:19], v[2:3], off offset:96
	v_lshlrev_b32_e32 v4, 16, v58
	v_and_b32_e32 v5, 0xffff0000, v58
	v_mul_f32_e32 v2, 0xbfb8aa3b, v4
	v_exp_f32_e32 v2, v2
	s_nop 0
	v_add_f32_e32 v2, 1.0, v2
	v_rcp_f32_e32 v6, v2
	v_mul_f32_e32 v2, 0xbfb8aa3b, v5
	v_exp_f32_e32 v2, v2
	s_nop 0
	v_add_f32_e32 v2, 1.0, v2
	v_rcp_f32_e32 v7, v2
	s_nop 0
	v_pk_mul_f32 v[4:5], v[6:7], v[4:5]
	s_nop 0
	v_pk_mul_f32 v[4:5], v[8:9], v[4:5]
	v_pk_mul_f32 v[8:9], v[16:17], v[0:1] op_sel_hi:[1,0]
	v_cvt_pk_bf16_f32 v2, v4, v5
	v_lshlrev_b32_e32 v4, 16, v59
	v_and_b32_e32 v5, 0xffff0000, v59
	v_mul_f32_e32 v3, 0xbfb8aa3b, v4
	v_mul_f32_e32 v0, 0xbfb8aa3b, v5
	v_exp_f32_e32 v3, v3
	v_exp_f32_e32 v0, v0
	v_add_f32_e32 v3, 1.0, v3
	v_add_f32_e32 v0, 1.0, v0
	v_rcp_f32_e32 v6, v3
	v_rcp_f32_e32 v7, v0
	s_nop 0
	v_pk_mul_f32 v[4:5], v[6:7], v[4:5]
	s_nop 0
	v_pk_mul_f32 v[4:5], v[8:9], v[4:5]
	s_nop 0
	v_cvt_pk_bf16_f32 v3, v4, v5
	global_store_dwordx2 v[18:19], v[2:3], off offset:112
	s_barrier
	s_and_saveexec_b64 s[74:75], s[92:93]
	s_cbranch_execz .LBB0_909
	s_mov_b64 s[78:79], exec
	v_mbcnt_lo_u32_b32 v0, s78, 0
	v_mbcnt_hi_u32_b32 v0, s79, v0
	v_cmp_eq_u32_e32 vcc, 0, v0
	s_and_saveexec_b64 s[2:3], vcc
	s_cbranch_execz .LBB0_908
	s_bcnt1_i32_b64 s70, s[78:79]
	v_readlane_b32 s0, v254, 51
	v_mov_b32_e32 v2, s70
	v_readlane_b32 s1, v254, 52
	s_nop 4
	global_atomic_add v2, v1, v2, s[0:1] offset:512 sc0
	s_branch .LBB0_908

; #define MFMA(a, b, c) __builtin_amdgcn_mfma_f32_32x32x16_bf16((a), (b), (c), 0, 0, 0)
; DI unsigned pack2(float a, float b) { f32v2 v = {a, b}; return __builtin_bit_cast(unsigned, __builtin_convertvector(v, bf16v2)); }
; DI float xhalf_sum(float v) { auto r = __builtin_amdgcn_permlane32_swap(__float_as_uint(v), __float_as_uint(v), false, false); return __uint_as_float(r[0]) + __uint_as_float(r[1]); }
; #define LSTORE(bf) { *(uint4*)&Ks[bf][kr0][kc0] = rk0; *(uint4*)&Ks[bf][kr1][kc1] = rk1; if (NKC == 3) *(uint4*)&Ks[bf][kr2][kc2] = rk2; \
;     *(uint2*)&Vs[bf][vd0][vk0] = make_uint2(rv0.x, rv0.y); *(uint2*)&Vs[bf][vd0][vk0 + 4] = make_uint2(rv0.z, rv0.w); \
;     *(uint2*)&Vs[bf][vd0 + 32][vk0] = make_uint2(rv1.x, rv1.y); *(uint2*)&Vs[bf][vd0 + 32][vk0 + 4] = make_uint2(rv1.z, rv1.w); }
; template <int DK, bool NA> ...
;     ...
;       float ls = 0.f;
; #pragma unroll
;       for (int kb = 0; kb < 2; kb++)
; #pragma unroll
;         for (int i = 0; i < 16; i++) { float pv = __builtin_amdgcn_exp2f(s[kb][i] - mn); s[kb][i] = pv; ls += pv; }
;       l_run += ls;
;       bf16x8 pf[2][2];
; #pragma unroll
;       for (int kb = 0; kb < 2; kb++)
; #pragma unroll
;         for (int sx = 0; sx < 2; sx++) {
;           uint4 u; u.x = pack2(s[kb][8 * sx], s[kb][8 * sx + 1]); u.y = pack2(s[kb][8 * sx + 2], s[kb][8 * sx + 3]);
;           u.z = pack2(s[kb][8 * sx + 4], s[kb][8 * sx + 5]); u.w = pack2(s[kb][8 * sx + 6], s[kb][8 * sx + 7]);
;           pf[kb][sx] = __builtin_bit_cast(bf16x8, u);
;         }
; #pragma unroll
;       for (int db = 0; db < 2; db++)
; #pragma unroll
;         for (int kb = 0; kb < 2; kb++)
; #pragma unroll
;           for (int sx = 0; sx < 2; sx++) {
;             const u16* vp = &Vs[buf][db * 32 + r][32 * kb + 16 * sx + 4 * h];
;             uint2 lo = *(const uint2*)vp, hi = *(const uint2*)(vp + 8);
;             uint4 u; u.x = lo.x; u.y = lo.y; u.z = hi.x; u.w = hi.y;
;             o[db] = MFMA(__builtin_bit_cast(bf16x8, u), pf[kb][sx], o[db]);
;           }
;     }
;     if (t + 1 < nTiles) LSTORE(buf ^ 1);
;     __syncthreads();
;   }
;     ...
;   const float lt = xhalf_sum(l_run);
.LBB0_1025:
	v_readlane_b32 s2, v253, 48
	v_lshlrev_b64 v[66:67], 11, v[128:129]
	v_readlane_b32 s3, v253, 49
	v_lshlrev_b32_e32 v0, 1, v0
	v_sub_f32_e32 v34, v34, v123
	v_lshl_add_u64 v[66:67], s[2:3], 0, v[66:67]
	v_lshl_add_u64 v[66:67], v[66:67], 0, v[0:1]
	v_sub_f32_e32 v0, v50, v123
	v_sub_f32_e32 v50, v51, v123
	v_exp_f32_e32 v68, v50
	v_sub_f32_e32 v50, v52, v123
	v_exp_f32_e32 v69, v50
	v_sub_f32_e32 v50, v53, v123
	v_exp_f32_e32 v70, v50
	v_sub_f32_e32 v50, v54, v123
	v_exp_f32_e32 v71, v50
	v_sub_f32_e32 v50, v55, v123
	v_exp_f32_e32 v75, v34
	v_sub_f32_e32 v34, v35, v123
	v_exp_f32_e32 v72, v50
	v_sub_f32_e32 v50, v56, v123
	v_exp_f32_e32 v76, v34
	v_sub_f32_e32 v34, v36, v123
	v_exp_f32_e32 v73, v50
	v_sub_f32_e32 v50, v57, v123
	v_exp_f32_e32 v77, v34
	v_sub_f32_e32 v34, v37, v123
	v_exp_f32_e32 v74, v50
	v_sub_f32_e32 v50, v58, v123
	v_exp_f32_e32 v78, v34
	v_sub_f32_e32 v34, v38, v123
	v_exp_f32_e32 v58, v50
	v_sub_f32_e32 v50, v59, v123
	v_exp_f32_e32 v79, v34
	v_sub_f32_e32 v34, v39, v123
	v_exp_f32_e32 v59, v50
	v_sub_f32_e32 v50, v60, v123
	v_exp_f32_e32 v80, v34
	v_sub_f32_e32 v34, v40, v123
	v_exp_f32_e32 v60, v50
	v_sub_f32_e32 v50, v61, v123
	v_exp_f32_e32 v81, v34
	v_sub_f32_e32 v34, v41, v123
	v_exp_f32_e32 v61, v50
	v_sub_f32_e32 v50, v62, v123
	v_exp_f32_e32 v83, v34
	v_sub_f32_e32 v34, v42, v123
	v_exp_f32_e32 v62, v50
	v_sub_f32_e32 v50, v63, v123
	v_exp_f32_e32 v84, v34
	v_sub_f32_e32 v34, v43, v123
	v_exp_f32_e32 v63, v50
	v_sub_f32_e32 v50, v64, v123
	v_exp_f32_e32 v85, v34
	v_sub_f32_e32 v34, v44, v123
	v_mad_u32_u24 v82, v82, s9, v143
	v_exp_f32_e32 v0, v0
	v_exp_f32_e32 v64, v50
	v_sub_f32_e32 v50, v65, v123
	v_exp_f32_e32 v86, v34
	v_sub_f32_e32 v34, v45, v123
	v_add_u32_e32 v92, 0x4800, v82
	v_exp_f32_e32 v65, v50
	v_exp_f32_e32 v87, v34
	v_sub_f32_e32 v34, v46, v123
	ds_read2_b64 v[50:53], v92 offset1:2
	ds_read2_b64 v[54:57], v92 offset0:4 offset1:6
	v_exp_f32_e32 v88, v34
	v_sub_f32_e32 v34, v47, v123
	v_exp_f32_e32 v89, v34
	v_sub_f32_e32 v34, v48, v123
	v_exp_f32_e32 v90, v34
	v_sub_f32_e32 v34, v49, v123
	v_cvt_pk_bf16_f32 v46, v0, v68
	v_cvt_pk_bf16_f32 v47, v69, v70
	v_cvt_pk_bf16_f32 v48, v71, v72
	v_cvt_pk_bf16_f32 v49, v73, v74
	v_cvt_pk_bf16_f32 v38, v58, v59
	v_cvt_pk_bf16_f32 v39, v60, v61
	s_waitcnt lgkmcnt(1)
	v_mfma_f32_32x32x16_bf16 v[18:33], v[50:53], v[46:49], v[18:33]
	v_cvt_pk_bf16_f32 v40, v62, v63
	v_cvt_pk_bf16_f32 v41, v64, v65
	ds_read2_b64 v[50:53], v92 offset0:8 offset1:10
	v_cvt_pk_bf16_f32 v42, v75, v76
	v_cvt_pk_bf16_f32 v43, v77, v78
	v_cvt_pk_bf16_f32 v44, v79, v80
	v_cvt_pk_bf16_f32 v45, v81, v83
	s_waitcnt lgkmcnt(1)
	v_mfma_f32_32x32x16_bf16 v[18:33], v[54:57], v[38:41], v[18:33]
	v_exp_f32_e32 v91, v34
	v_cvt_pk_bf16_f32 v34, v84, v85
	v_cvt_pk_bf16_f32 v35, v86, v87
	v_cvt_pk_bf16_f32 v36, v88, v89
	v_cvt_pk_bf16_f32 v37, v90, v91
	v_add_u32_e32 v54, 0x5800, v82
	v_add_f32_e32 v0, 0, v0
	s_waitcnt lgkmcnt(0)
	v_mfma_f32_32x32x16_bf16 v[18:33], v[50:53], v[42:45], v[18:33]
	ds_read2_b64 v[50:53], v92 offset0:12 offset1:14
	v_add_f32_e32 v0, v68, v0
	v_add_f32_e32 v0, v69, v0
	v_add_f32_e32 v0, v70, v0
	v_add_f32_e32 v0, v71, v0
	v_add_f32_e32 v0, v72, v0
	v_add_f32_e32 v0, v73, v0
	s_waitcnt lgkmcnt(0)
	v_mfma_f32_32x32x16_bf16 v[18:33], v[50:53], v[34:37], v[18:33]
	ds_read2_b64 v[50:53], v54 offset0:32 offset1:34
	v_add_f32_e32 v0, v74, v0
	v_add_f32_e32 v0, v58, v0
	v_add_f32_e32 v0, v59, v0
	v_add_f32_e32 v0, v60, v0
	v_add_f32_e32 v0, v61, v0
	v_add_f32_e32 v0, v62, v0
	s_waitcnt lgkmcnt(0)
	v_mfma_f32_32x32x16_bf16 v[2:17], v[50:53], v[46:49], v[2:17]
	ds_read2_b64 v[46:49], v54 offset0:36 offset1:38
	v_add_f32_e32 v0, v63, v0
	v_add_f32_e32 v0, v64, v0
	v_add_f32_e32 v0, v65, v0
	v_add_f32_e32 v0, v75, v0
	v_add_f32_e32 v0, v76, v0
	v_add_f32_e32 v0, v77, v0
	s_waitcnt lgkmcnt(0)
	v_mfma_f32_32x32x16_bf16 v[2:17], v[46:49], v[38:41], v[2:17]
	ds_read2_b64 v[38:41], v54 offset0:40 offset1:42
	v_add_f32_e32 v0, v78, v0
	v_add_f32_e32 v0, v79, v0
	v_add_f32_e32 v0, v80, v0
	v_add_f32_e32 v0, v81, v0
	v_add_f32_e32 v0, v83, v0
	v_add_f32_e32 v0, v84, v0
	s_waitcnt lgkmcnt(0)
	v_mfma_f32_32x32x16_bf16 v[2:17], v[38:41], v[42:45], v[2:17]
	ds_read2_b64 v[38:41], v54 offset0:44 offset1:46
	v_add_f32_e32 v0, v85, v0
	v_add_f32_e32 v0, v86, v0
	v_add_f32_e32 v0, v87, v0
	v_add_f32_e32 v0, v88, v0
	v_add_f32_e32 v0, v89, v0
	v_add_f32_e32 v0, v90, v0
	v_add_f32_e32 v0, v91, v0
	v_add_f32_e32 v0, v121, v0
	s_waitcnt lgkmcnt(0)
	v_mfma_f32_32x32x16_bf16 v[2:17], v[38:41], v[34:37], v[2:17]
	v_mov_b32_e32 v34, v0
	s_nop 1
	v_permlane32_swap_b32_e32 v0, v34
	v_mov_b32_e32 v125, v1
	v_add_f32_e32 v0, v0, v34
	v_lshl_add_u64 v[34:35], v[126:127], 0, v[124:125]
	s_barrier
; DI unsigned pack2(float a, float b) { f32v2 v = {a, b}; return __builtin_bit_cast(unsigned, __builtin_convertvector(v, bf16v2)); }
; DI float bflo(unsigned v) { return __uint_as_float(v << 16); }
; DI float bfhi(unsigned v) { return __uint_as_float(v & 0xffff0000u); }
; DI float silu(float x) { return x * sigm(x); }
; DI float xhalf_sum(float v) { auto r = __builtin_amdgcn_permlane32_swap(__float_as_uint(v), __float_as_uint(v), false, false); return __uint_as_float(r[0]) + __uint_as_float(r[1]); }
; template <int DK, bool NA> ...
;     ...
;   const float lt = xhalf_sum(l_run);
;   const float inv = __builtin_amdgcn_rcpf(lt);
;   const int q = w * 32 + r;
; #pragma unroll
;   for (int db = 0; db < 2; db++)
; #pragma unroll
;     for (int g = 0; g < 4; g++) {
;       const int d0 = 32 * db + 8 * g + 4 * h;
;       uint2 zz = *(const uint2*)(Zp + (size_t)q * PKW + d0);
;       uint2 ov; ov.x = pack2(o[db][4 * g] * inv * silu(bflo(zz.x)), o[db][4 * g + 1] * inv * silu(bfhi(zz.x)));
;       ov.y = pack2(o[db][4 * g + 2] * inv * silu(bflo(zz.y)), o[db][4 * g + 3] * inv * silu(bfhi(zz.y)));
;       *(uint2*)(Gp + (size_t)q * 1024 + d0) = ov;
;     }
	global_load_dwordx2 v[44:45], v[34:35], off offset:1536
	global_load_dwordx2 v[46:47], v[34:35], off offset:1552
	global_load_dwordx2 v[48:49], v[34:35], off offset:1568
	global_load_dwordx2 v[50:51], v[34:35], off offset:1584
	global_load_dwordx2 v[52:53], v[34:35], off offset:1600
	global_load_dwordx2 v[54:55], v[34:35], off offset:1616
	global_load_dwordx2 v[56:57], v[34:35], off offset:1632
	global_load_dwordx2 v[58:59], v[34:35], off offset:1648
	v_rcp_f32_e32 v0, v0
	v_lshl_add_u64 v[36:37], v[66:67], 0, v[112:113]
	v_pk_mul_f32 v[18:19], v[18:19], v[0:1] op_sel_hi:[1,0]
	v_pk_mul_f32 v[20:21], v[20:21], v[0:1] op_sel_hi:[1,0]
	v_pk_mul_f32 v[22:23], v[22:23], v[0:1] op_sel_hi:[1,0]
	v_pk_mul_f32 v[24:25], v[24:25], v[0:1] op_sel_hi:[1,0]
	v_pk_mul_f32 v[26:27], v[26:27], v[0:1] op_sel_hi:[1,0]
	v_pk_mul_f32 v[2:3], v[2:3], v[0:1] op_sel_hi:[1,0]
	v_pk_mul_f32 v[4:5], v[4:5], v[0:1] op_sel_hi:[1,0]
	v_pk_mul_f32 v[6:7], v[6:7], v[0:1] op_sel_hi:[1,0]
	v_pk_mul_f32 v[8:9], v[8:9], v[0:1] op_sel_hi:[1,0]
	s_waitcnt vmcnt(0)
	v_lshlrev_b32_e32 v40, 16, v44
	v_and_b32_e32 v41, 0xffff0000, v44
	v_mul_f32_e32 v38, 0xbfb8aa3b, v40
	v_exp_f32_e32 v38, v38
	s_nop 0
	v_add_f32_e32 v38, 1.0, v38
	v_rcp_f32_e32 v42, v38
	v_mul_f32_e32 v38, 0xbfb8aa3b, v41
	v_exp_f32_e32 v38, v38
	s_nop 0
	v_add_f32_e32 v38, 1.0, v38
	v_rcp_f32_e32 v43, v38
	s_nop 0
	v_pk_mul_f32 v[40:41], v[42:43], v[40:41]
	s_nop 0
	v_pk_mul_f32 v[18:19], v[18:19], v[40:41]
	s_nop 0
	v_cvt_pk_bf16_f32 v38, v18, v19
	v_lshlrev_b32_e32 v18, 16, v45
	v_and_b32_e32 v19, 0xffff0000, v45
	v_mul_f32_e32 v39, 0xbfb8aa3b, v18
	v_exp_f32_e32 v39, v39
	s_nop 0
	v_add_f32_e32 v39, 1.0, v39
	v_rcp_f32_e32 v40, v39
	v_mul_f32_e32 v39, 0xbfb8aa3b, v19
	v_exp_f32_e32 v39, v39
	s_nop 0
	v_add_f32_e32 v39, 1.0, v39
	v_rcp_f32_e32 v41, v39
	s_nop 0
	v_pk_mul_f32 v[18:19], v[40:41], v[18:19]
	s_nop 0
	v_pk_mul_f32 v[18:19], v[20:21], v[18:19]
	v_cvt_pk_bf16_f32 v39, v18, v19
	v_lshl_add_u64 v[18:19], v[36:37], 0, v[124:125]
	global_store_dwordx2 v[18:19], v[38:39], off
	s_waitcnt vmcnt(1)
	v_lshlrev_b32_e32 v36, 16, v46
	v_and_b32_e32 v37, 0xffff0000, v46
	v_mul_f32_e32 v20, 0xbfb8aa3b, v36
	v_exp_f32_e32 v20, v20
	s_nop 0
	v_add_f32_e32 v20, 1.0, v20
	v_rcp_f32_e32 v38, v20
	v_mul_f32_e32 v20, 0xbfb8aa3b, v37
	v_exp_f32_e32 v20, v20
	s_nop 0
	v_add_f32_e32 v20, 1.0, v20
	v_rcp_f32_e32 v39, v20
	s_nop 0
	v_pk_mul_f32 v[36:37], v[38:39], v[36:37]
	s_nop 0
	v_pk_mul_f32 v[22:23], v[22:23], v[36:37]
	s_nop 0
	v_cvt_pk_bf16_f32 v20, v22, v23
	v_lshlrev_b32_e32 v22, 16, v47
	v_and_b32_e32 v23, 0xffff0000, v47
	v_mul_f32_e32 v21, 0xbfb8aa3b, v22
	v_exp_f32_e32 v21, v21
	s_nop 0
	v_add_f32_e32 v21, 1.0, v21
	v_rcp_f32_e32 v36, v21
	v_mul_f32_e32 v21, 0xbfb8aa3b, v23
	v_exp_f32_e32 v21, v21
	s_nop 0
	v_add_f32_e32 v21, 1.0, v21
	v_rcp_f32_e32 v37, v21
	s_nop 0
	v_pk_mul_f32 v[22:23], v[36:37], v[22:23]
	s_nop 0
	v_pk_mul_f32 v[22:23], v[24:25], v[22:23]
	s_nop 0
	v_cvt_pk_bf16_f32 v21, v22, v23
	global_store_dwordx2 v[18:19], v[20:21], off offset:16
	v_lshlrev_b32_e32 v22, 16, v48
	v_and_b32_e32 v23, 0xffff0000, v48
	v_mul_f32_e32 v20, 0xbfb8aa3b, v22
	v_exp_f32_e32 v20, v20
	s_nop 0
	v_add_f32_e32 v20, 1.0, v20
	v_rcp_f32_e32 v24, v20
	v_mul_f32_e32 v20, 0xbfb8aa3b, v23
	v_exp_f32_e32 v20, v20
	s_nop 0
	v_add_f32_e32 v20, 1.0, v20
	v_rcp_f32_e32 v25, v20
	s_nop 0
	v_pk_mul_f32 v[22:23], v[24:25], v[22:23]
	s_nop 0
	v_pk_mul_f32 v[22:23], v[26:27], v[22:23]
	v_pk_mul_f32 v[26:27], v[28:29], v[0:1] op_sel_hi:[1,0]
	v_cvt_pk_bf16_f32 v20, v22, v23
	v_lshlrev_b32_e32 v22, 16, v49
	v_and_b32_e32 v23, 0xffff0000, v49
	v_mul_f32_e32 v21, 0xbfb8aa3b, v22
	v_exp_f32_e32 v21, v21
	s_nop 0
	v_add_f32_e32 v21, 1.0, v21
	v_rcp_f32_e32 v24, v21
	v_mul_f32_e32 v21, 0xbfb8aa3b, v23
	v_exp_f32_e32 v21, v21
	s_nop 0
	v_add_f32_e32 v21, 1.0, v21
	v_rcp_f32_e32 v25, v21
	s_nop 0
	v_pk_mul_f32 v[22:23], v[24:25], v[22:23]
	s_nop 0
	v_pk_mul_f32 v[22:23], v[26:27], v[22:23]
	v_pk_mul_f32 v[26:27], v[30:31], v[0:1] op_sel_hi:[1,0]
	v_cvt_pk_bf16_f32 v21, v22, v23
	global_store_dwordx2 v[18:19], v[20:21], off offset:32
	v_lshlrev_b32_e32 v22, 16, v50
	v_and_b32_e32 v23, 0xffff0000, v50
	v_mul_f32_e32 v20, 0xbfb8aa3b, v22
	v_exp_f32_e32 v20, v20
	s_nop 0
	v_add_f32_e32 v20, 1.0, v20
	v_rcp_f32_e32 v24, v20
	v_mul_f32_e32 v20, 0xbfb8aa3b, v23
	v_exp_f32_e32 v20, v20
	s_nop 0
	v_add_f32_e32 v20, 1.0, v20
	v_rcp_f32_e32 v25, v20
	s_nop 0
	v_pk_mul_f32 v[22:23], v[24:25], v[22:23]
	s_nop 0
	v_pk_mul_f32 v[22:23], v[26:27], v[22:23]
	v_pk_mul_f32 v[26:27], v[32:33], v[0:1] op_sel_hi:[1,0]
	v_cvt_pk_bf16_f32 v20, v22, v23
	v_lshlrev_b32_e32 v22, 16, v51
	v_and_b32_e32 v23, 0xffff0000, v51
; DI unsigned pack2(float a, float b) { f32v2 v = {a, b}; return __builtin_bit_cast(unsigned, __builtin_convertvector(v, bf16v2)); }
; DI float bflo(unsigned v) { return __uint_as_float(v << 16); }
; DI float bfhi(unsigned v) { return __uint_as_float(v & 0xffff0000u); }
; DI float silu(float x) { return x * sigm(x); }
; template <int DK, bool NA> ...
;     ...
; #pragma unroll
;   for (int db = 0; db < 2; db++)
; #pragma unroll
;     for (int g = 0; g < 4; g++) {
;       const int d0 = 32 * db + 8 * g + 4 * h;
;       uint2 zz = *(const uint2*)(Zp + (size_t)q * PKW + d0);
;       uint2 ov; ov.x = pack2(o[db][4 * g] * inv * silu(bflo(zz.x)), o[db][4 * g + 1] * inv * silu(bfhi(zz.x)));
;       ov.y = pack2(o[db][4 * g + 2] * inv * silu(bflo(zz.y)), o[db][4 * g + 3] * inv * silu(bfhi(zz.y)));
;       *(uint2*)(Gp + (size_t)q * 1024 + d0) = ov;
;     }
; DI int fetch_item(unsigned* ctr, char* smem) {
;   volatile int* slot = (volatile int*)(smem + SMEM_BYTES - 16);
;   __syncthreads();
;   if (threadIdx.x == 0) *slot = (int)__hip_atomic_fetch_add(ctr, 1u, __ATOMIC_RELAXED, __HIP_MEMORY_SCOPE_AGENT);
;   __syncthreads();
;   return *slot;
; }
	v_mul_f32_e32 v21, 0xbfb8aa3b, v22
	v_exp_f32_e32 v21, v21
	s_nop 0
	v_add_f32_e32 v21, 1.0, v21
	v_rcp_f32_e32 v24, v21
	v_mul_f32_e32 v21, 0xbfb8aa3b, v23
	v_exp_f32_e32 v21, v21
	s_nop 0
	v_add_f32_e32 v21, 1.0, v21
	v_rcp_f32_e32 v25, v21
	s_nop 0
	v_pk_mul_f32 v[22:23], v[24:25], v[22:23]
	s_nop 0
	v_pk_mul_f32 v[22:23], v[26:27], v[22:23]
	s_nop 0
	v_cvt_pk_bf16_f32 v21, v22, v23
	global_store_dwordx2 v[18:19], v[20:21], off offset:48
	v_lshlrev_b32_e32 v22, 16, v52
	v_and_b32_e32 v23, 0xffff0000, v52
	v_mul_f32_e32 v20, 0xbfb8aa3b, v22
	v_exp_f32_e32 v20, v20
	s_nop 0
	v_add_f32_e32 v20, 1.0, v20
	v_rcp_f32_e32 v24, v20
	v_mul_f32_e32 v20, 0xbfb8aa3b, v23
	v_exp_f32_e32 v20, v20
	s_nop 0
	v_add_f32_e32 v20, 1.0, v20
	v_rcp_f32_e32 v25, v20
	v_lshlrev_b32_e32 v20, 16, v53
	v_and_b32_e32 v21, 0xffff0000, v53
	v_pk_mul_f32 v[22:23], v[24:25], v[22:23]
	s_nop 0
	v_pk_mul_f32 v[2:3], v[2:3], v[22:23]
	s_nop 0
	v_cvt_pk_bf16_f32 v2, v2, v3
	v_mul_f32_e32 v3, 0xbfb8aa3b, v20
	v_exp_f32_e32 v3, v3
	s_nop 0
	v_add_f32_e32 v3, 1.0, v3
	v_rcp_f32_e32 v22, v3
	v_mul_f32_e32 v3, 0xbfb8aa3b, v21
	v_exp_f32_e32 v3, v3
	s_nop 0
	v_add_f32_e32 v3, 1.0, v3
	v_rcp_f32_e32 v23, v3
	s_nop 0
	v_pk_mul_f32 v[20:21], v[22:23], v[20:21]
	s_nop 0
	v_pk_mul_f32 v[4:5], v[4:5], v[20:21]
	s_nop 0
	v_cvt_pk_bf16_f32 v3, v4, v5
	global_store_dwordx2 v[18:19], v[2:3], off offset:64
	v_lshlrev_b32_e32 v4, 16, v54
	v_and_b32_e32 v5, 0xffff0000, v54
	v_mul_f32_e32 v2, 0xbfb8aa3b, v4
	v_exp_f32_e32 v2, v2
	s_nop 0
	v_add_f32_e32 v2, 1.0, v2
	v_rcp_f32_e32 v20, v2
	v_mul_f32_e32 v2, 0xbfb8aa3b, v5
	v_exp_f32_e32 v2, v2
	s_nop 0
	v_add_f32_e32 v2, 1.0, v2
	v_rcp_f32_e32 v21, v2
	s_nop 0
	v_pk_mul_f32 v[4:5], v[20:21], v[4:5]
	s_nop 0
	v_pk_mul_f32 v[4:5], v[6:7], v[4:5]
	s_nop 0
	v_cvt_pk_bf16_f32 v2, v4, v5
	v_lshlrev_b32_e32 v4, 16, v55
	v_and_b32_e32 v5, 0xffff0000, v55
	v_mul_f32_e32 v3, 0xbfb8aa3b, v4
	v_exp_f32_e32 v3, v3
	s_nop 0
	v_add_f32_e32 v3, 1.0, v3
	v_rcp_f32_e32 v6, v3
	v_mul_f32_e32 v3, 0xbfb8aa3b, v5
	v_exp_f32_e32 v3, v3
	s_nop 0
	v_add_f32_e32 v3, 1.0, v3
	v_rcp_f32_e32 v7, v3
	s_nop 0
	v_pk_mul_f32 v[4:5], v[6:7], v[4:5]
	s_nop 0
	v_pk_mul_f32 v[4:5], v[8:9], v[4:5]
	v_pk_mul_f32 v[8:9], v[10:11], v[0:1] op_sel_hi:[1,0]
	v_cvt_pk_bf16_f32 v3, v4, v5
	global_store_dwordx2 v[18:19], v[2:3], off offset:80
	v_lshlrev_b32_e32 v4, 16, v56
	v_and_b32_e32 v5, 0xffff0000, v56
	v_mul_f32_e32 v2, 0xbfb8aa3b, v4
	v_exp_f32_e32 v2, v2
	s_nop 0
	v_add_f32_e32 v2, 1.0, v2
	v_rcp_f32_e32 v6, v2
	v_mul_f32_e32 v2, 0xbfb8aa3b, v5
	v_exp_f32_e32 v2, v2
	s_nop 0
	v_add_f32_e32 v2, 1.0, v2
	v_rcp_f32_e32 v7, v2
	s_nop 0
	v_pk_mul_f32 v[4:5], v[6:7], v[4:5]
	s_nop 0
	v_pk_mul_f32 v[4:5], v[8:9], v[4:5]
	v_pk_mul_f32 v[8:9], v[12:13], v[0:1] op_sel_hi:[1,0]
	v_cvt_pk_bf16_f32 v2, v4, v5
	v_lshlrev_b32_e32 v4, 16, v57
	v_and_b32_e32 v5, 0xffff0000, v57
	v_mul_f32_e32 v3, 0xbfb8aa3b, v4
	v_exp_f32_e32 v3, v3
	s_nop 0
	v_add_f32_e32 v3, 1.0, v3
	v_rcp_f32_e32 v6, v3
	v_mul_f32_e32 v3, 0xbfb8aa3b, v5
	v_exp_f32_e32 v3, v3
	s_nop 0
	v_add_f32_e32 v3, 1.0, v3
	v_rcp_f32_e32 v7, v3
	s_nop 0
	v_pk_mul_f32 v[4:5], v[6:7], v[4:5]
	s_nop 0
	v_pk_mul_f32 v[4:5], v[8:9], v[4:5]
	v_pk_mul_f32 v[8:9], v[14:15], v[0:1] op_sel_hi:[1,0]
	v_cvt_pk_bf16_f32 v3, v4, v5
	global_store_dwordx2 v[18:19], v[2:3], off offset:96
	v_lshlrev_b32_e32 v4, 16, v58
	v_and_b32_e32 v5, 0xffff0000, v58
	v_mul_f32_e32 v2, 0xbfb8aa3b, v4
	v_exp_f32_e32 v2, v2
	s_nop 0
	v_add_f32_e32 v2, 1.0, v2
	v_rcp_f32_e32 v6, v2
	v_mul_f32_e32 v2, 0xbfb8aa3b, v5
	v_exp_f32_e32 v2, v2
	s_nop 0
	v_add_f32_e32 v2, 1.0, v2
	v_rcp_f32_e32 v7, v2
	s_nop 0
	v_pk_mul_f32 v[4:5], v[6:7], v[4:5]
	s_nop 0
	v_pk_mul_f32 v[4:5], v[8:9], v[4:5]
	v_pk_mul_f32 v[8:9], v[16:17], v[0:1] op_sel_hi:[1,0]
	v_cvt_pk_bf16_f32 v2, v4, v5
	v_lshlrev_b32_e32 v4, 16, v59
	v_and_b32_e32 v5, 0xffff0000, v59
	v_mul_f32_e32 v3, 0xbfb8aa3b, v4
	v_mul_f32_e32 v0, 0xbfb8aa3b, v5
	v_exp_f32_e32 v3, v3
	v_exp_f32_e32 v0, v0
	v_add_f32_e32 v3, 1.0, v3
	v_add_f32_e32 v0, 1.0, v0
	v_rcp_f32_e32 v6, v3
	v_rcp_f32_e32 v7, v0
	s_nop 0
	v_pk_mul_f32 v[4:5], v[6:7], v[4:5]
	s_nop 0
	v_pk_mul_f32 v[4:5], v[8:9], v[4:5]
	s_nop 0
	v_cvt_pk_bf16_f32 v3, v4, v5
	global_store_dwordx2 v[18:19], v[2:3], off offset:112
	s_barrier
	s_and_saveexec_b64 s[6:7], s[92:93]
	s_cbranch_execz .LBB0_1014
	s_mov_b64 s[8:9], exec
	v_mbcnt_lo_u32_b32 v0, s8, 0
	v_mbcnt_hi_u32_b32 v0, s9, v0
	v_cmp_eq_u32_e32 vcc, 0, v0
	s_and_saveexec_b64 s[2:3], vcc
	s_cbranch_execz .LBB0_1013
	s_bcnt1_i32_b64 s8, s[8:9]
	v_mov_b32_e32 v2, s8
	v_readlane_b32 s8, v254, 51
	v_readlane_b32 s9, v254, 52
	s_nop 4
	global_atomic_add v2, v1, v2, s[8:9] offset:768 sc0
	s_branch .LBB0_1013
